# S5 Bbar and C tables also written by P0 in MFMA-fragment order (contiguous 1 KiB per fragment) and read that way by the prompt-tile S5 code in P5 and P6
# speedup vs baseline: 1.0114x; 1.0030x over previous
;     __device__ __forceinline__ const float* in(int i) const { return karg_in(i); }
; __device__ __forceinline__ double dexp(double x) {
;     const double y = x * (1.0 / 256.0); double t = 1.0;
; #pragma unroll
;     for (int i = 12; i >= 1; --i) t = 1.0 + t * y * (1.0 / (double)i);
; #pragma unroll
;     for (int i = 0; i < 8; ++i) t = t * t;
;     return t;
; }
; __device__ __forceinline__ void dsincos(double x, double& s, double& c) {
;     const double twopi = 6.283185307179586476925286766559;
;     const double k = rint(x * (1.0 / twopi)); const double r = x - k * twopi, r2 = r * r;
;     double ts = r, tc = 1.0; s = r; c = 1.0;
; #pragma unroll
;     for (int i = 1; i <= 15; ++i) { tc = -tc * r2 * (1.0 / (double)((2 * i - 1) * (2 * i))); ts = -ts * r2 * (1.0 / (double)((2 * i) * (2 * i + 1))); c += tc; s += ts; }
; }
; __device__ __forceinline__ void p0_prologue(const Ctx& C, LAS unsigned char* lds, int wave, int lane, int tid) {
;     ...
;     for (int idx = (tid < 8 ? blockIdx.x * 8 + tid : NG * NP); idx < NG * NP; idx += gridDim.x * 8) {
;         const int g = idx / NP, p = idx % NP;
;         const double lr = (double)C.in(14)[idx], li = (double)C.in(15)[idx], dt = dexp((double)C.in(16)[g]);
;         double s1, c1, s8, c8; dsincos(li * dt, s1, c1); dsincos(li * dt * 128.0, s8, c8);
;         const double er = dexp(lr * dt), lbr = er * c1, lbi = er * s1;
;         const double e8 = dexp(lr * dt * 128.0), l8r = e8 * c8, l8i = e8 * s8;
.LBB0_126:
	s_mov_b64 s[42:43], s[80:81]
	s_load_dwordx2 s[42:43], s[42:43], 0x70
	v_ashrrev_i32_e32 v3, 31, v2
	v_lshlrev_b64 v[8:9], 2, v[2:3]
	s_mov_b64 s[0:1], s[80:81]
	s_mov_b32 s74, s64
	s_waitcnt lgkmcnt(0)
	v_lshl_add_u64 v[4:5], s[42:43], 0, v[8:9]
	global_load_dword v11, v[4:5], off
	s_load_dwordx2 s[0:1], s[0:1], 0x78
	s_mov_b64 s[42:43], s[80:81]
	s_waitcnt lgkmcnt(0)
	v_lshl_add_u64 v[4:5], s[0:1], 0, v[8:9]
	global_load_dword v14, v[4:5], off
	s_load_dwordx2 s[0:1], s[42:43], 0x80
	v_lshrrev_b32_e32 v4, 26, v3
	v_add_u32_e32 v10, v2, v4
	v_ashrrev_i32_e32 v6, 6, v10
	v_ashrrev_i32_e32 v7, 31, v6
	s_waitcnt lgkmcnt(0)
	v_lshl_add_u64 v[4:5], v[6:7], 2, s[0:1]
	global_load_dword v16, v[4:5], off
	s_mov_b64 s[0:1], s[80:81]
	s_load_dwordx2 s[0:1], s[0:1], 0x110
	v_lshlrev_b64 v[4:5], 6, v[2:3]
	v_and_b32_e32 v3, 0xffffffc0, v10
	v_sub_u32_e32 v10, v2, v3
	v_lshlrev_b64 v[6:7], 12, v[6:7]
	s_mov_b64 s[42:43], 0
	s_waitcnt vmcnt(2)
	v_cvt_f64_f32_e32 v[12:13], v11
	v_ashrrev_i32_e32 v11, 31, v10
	s_waitcnt vmcnt(1)
	v_cvt_f64_f32_e32 v[14:15], v14
	s_waitcnt vmcnt(0)
	v_cvt_f64_f32_e32 v[16:17], v16
	v_ldexp_f64 v[16:17], v[16:17], -8
	v_fma_f64 v[18:19], v[16:17], s[8:9], 1.0
	v_mul_f64 v[18:19], v[16:17], v[18:19]
	v_fma_f64 v[18:19], v[18:19], s[12:13], 1.0
	v_mul_f64 v[18:19], v[16:17], v[18:19]
	v_fma_f64 v[18:19], v[18:19], s[14:15], 1.0
	v_mul_f64 v[18:19], v[16:17], v[18:19]
	v_fma_f64 v[18:19], v[18:19], s[16:17], 1.0
	v_mul_f64 v[18:19], v[16:17], v[18:19]
	v_fma_f64 v[18:19], v[18:19], s[18:19], 1.0
	v_mul_f64 v[18:19], v[16:17], v[18:19]
	v_fma_f64 v[18:19], v[18:19], s[20:21], 1.0
	v_mul_f64 v[18:19], v[16:17], v[18:19]
	v_fma_f64 v[18:19], v[18:19], s[22:23], 1.0
	v_mul_f64 v[18:19], v[16:17], v[18:19]
	v_fma_f64 v[18:19], v[18:19], s[24:25], 1.0
	v_mul_f64 v[18:19], v[16:17], v[18:19]
	v_fma_f64 v[18:19], v[18:19], s[26:27], 1.0
	v_mul_f64 v[18:19], v[16:17], v[18:19]
	v_fma_f64 v[18:19], v[18:19], s[28:29], 1.0
	v_mul_f64 v[18:19], v[16:17], v[18:19]
	v_fma_f64 v[18:19], v[18:19], 0.5, 1.0
	v_fma_f64 v[16:17], v[16:17], v[18:19], 1.0
	v_mul_f64 v[16:17], v[16:17], v[16:17]
	v_mul_f64 v[16:17], v[16:17], v[16:17]
	v_mul_f64 v[16:17], v[16:17], v[16:17]
	v_mul_f64 v[16:17], v[16:17], v[16:17]
	v_mul_f64 v[16:17], v[16:17], v[16:17]
	v_mul_f64 v[16:17], v[16:17], v[16:17]
	v_mul_f64 v[16:17], v[16:17], v[16:17]
	v_mul_f64 v[24:25], v[16:17], v[16:17]
	v_mul_f64 v[18:19], v[24:25], v[14:15]
	v_mul_f64 v[20:21], v[18:19], s[2:3]
	v_ldexp_f64 v[16:17], v[18:19], 7
	v_rndne_f64_e32 v[20:21], v[20:21]
	v_mul_f64 v[22:23], v[16:17], s[2:3]
	v_fma_f64 v[26:27], s[34:35], v[20:21], v[18:19]
	v_rndne_f64_e32 v[18:19], v[22:23]
	v_mul_f64 v[28:29], v[26:27], v[26:27]
	v_fmac_f64_e32 v[16:17], s[34:35], v[18:19]
	v_mul_f64 v[30:31], v[28:29], -v[26:27]
	v_mul_f64 v[22:23], v[28:29], 0.5
	v_mul_f64 v[20:21], v[16:17], v[16:17]
	v_mul_f64 v[32:33], v[30:31], s[22:23]
	v_fma_f64 v[18:19], v[28:29], -0.5, 1.0
	v_fmac_f64_e32 v[26:27], s[22:23], v[30:31]
	v_mul_f64 v[30:31], v[28:29], v[22:23]
	v_mul_f64 v[34:35], v[20:21], 0.5
	v_mul_f64 v[36:37], v[20:21], -v[16:17]
	v_mul_f64 v[32:33], v[28:29], -v[32:33]
	v_mul_f64 v[38:39], v[30:31], s[8:9]
	v_fmac_f64_e32 v[18:19], s[8:9], v[30:31]
	v_mul_f64 v[30:31], v[36:37], s[22:23]
	v_fmac_f64_e32 v[16:17], s[22:23], v[36:37]
	v_mul_f64 v[34:35], v[20:21], v[34:35]
	v_mul_f64 v[36:37], v[32:33], s[36:37]
	v_fma_f64 v[22:23], v[20:21], -0.5, 1.0
	v_fmac_f64_e32 v[26:27], s[36:37], v[32:33]
	v_mul_f64 v[32:33], v[28:29], -v[38:39]
	v_mul_f64 v[38:39], v[34:35], s[8:9]
	v_mul_f64 v[30:31], v[20:21], -v[30:31]
	v_mul_f64 v[36:37], v[28:29], -v[36:37]
	v_fmac_f64_e32 v[22:23], s[8:9], v[34:35]
	v_mul_f64 v[34:35], v[32:33], s[38:39]
	v_fmac_f64_e32 v[18:19], s[38:39], v[32:33]
	v_mul_f64 v[32:33], v[30:31], s[36:37]
	v_fmac_f64_e32 v[16:17], s[36:37], v[30:31]
	v_mul_f64 v[30:31], v[20:21], -v[38:39]
	v_mul_f64 v[38:39], v[36:37], s[48:49]
	v_mul_f64 v[34:35], v[28:29], -v[34:35]
	v_mul_f64 v[38:39], v[28:29], -v[38:39]
	v_fmac_f64_e32 v[26:27], s[48:49], v[36:37]
	v_mul_f64 v[40:41], v[34:35], s[50:51]
	v_fmac_f64_e32 v[18:19], s[50:51], v[34:35]
	v_mul_f64 v[34:35], v[38:39], s[52:53]
	v_fmac_f64_e32 v[26:27], s[52:53], v[38:39]
	v_mul_f64 v[38:39], v[28:29], -v[40:41]
	v_mul_f64 v[34:35], v[28:29], -v[34:35]
	v_mul_f64 v[40:41], v[38:39], s[54:55]
	v_fmac_f64_e32 v[18:19], s[54:55], v[38:39]
	v_mul_f64 v[38:39], v[34:35], s[56:57]
	v_fmac_f64_e32 v[26:27], s[56:57], v[34:35]
	v_mul_f64 v[34:35], v[28:29], -v[40:41]
	v_mul_f64 v[38:39], v[28:29], -v[38:39]
	v_mul_f64 v[40:41], v[34:35], s[58:59]
	v_fmac_f64_e32 v[18:19], s[58:59], v[34:35]
	v_mul_f64 v[34:35], v[38:39], s[60:61]
	v_fmac_f64_e32 v[26:27], s[60:61], v[38:39]
	v_mul_f64 v[38:39], v[28:29], -v[40:41]
	v_mul_f64 v[34:35], v[28:29], -v[34:35]
	v_mul_f64 v[40:41], v[38:39], s[62:63]
	v_fmac_f64_e32 v[18:19], s[62:63], v[38:39]
	v_mul_f64 v[38:39], v[34:35], s[64:65]
	v_fmac_f64_e32 v[26:27], s[64:65], v[34:35]
	v_mul_f64 v[34:35], v[28:29], -v[40:41]
	v_mul_f64 v[38:39], v[28:29], -v[38:39]
	v_mul_f64 v[40:41], v[34:35], s[40:41]
	v_fmac_f64_e32 v[18:19], s[40:41], v[34:35]
	v_mul_f64 v[34:35], v[38:39], s[66:67]
	v_fmac_f64_e32 v[26:27], s[66:67], v[38:39]
	v_mul_f64 v[38:39], v[28:29], -v[40:41]
	v_mul_f64 v[34:35], v[28:29], -v[34:35]
	v_mul_f64 v[40:41], v[38:39], s[68:69]
	v_fmac_f64_e32 v[18:19], s[68:69], v[38:39]
	v_mul_f64 v[38:39], v[34:35], s[4:5]
	v_fmac_f64_e32 v[26:27], s[4:5], v[34:35]
	v_mul_f64 v[34:35], v[28:29], -v[40:41]
	v_mul_f64 v[38:39], v[28:29], -v[38:39]
	v_mul_f64 v[40:41], v[34:35], s[72:73]
; __device__ __forceinline__ double dexp(double x) {
;     const double y = x * (1.0 / 256.0); double t = 1.0;
; #pragma unroll
;     for (int i = 12; i >= 1; --i) t = 1.0 + t * y * (1.0 / (double)i);
; #pragma unroll
;     for (int i = 0; i < 8; ++i) t = t * t;
;     return t;
; }
; __device__ __forceinline__ void dsincos(double x, double& s, double& c) {
;     const double twopi = 6.283185307179586476925286766559;
;     const double k = rint(x * (1.0 / twopi)); const double r = x - k * twopi, r2 = r * r;
;     double ts = r, tc = 1.0; s = r; c = 1.0;
; #pragma unroll
;     for (int i = 1; i <= 15; ++i) { tc = -tc * r2 * (1.0 / (double)((2 * i - 1) * (2 * i))); ts = -ts * r2 * (1.0 / (double)((2 * i) * (2 * i + 1))); c += tc; s += ts; }
; }
	v_fmac_f64_e32 v[18:19], s[72:73], v[34:35]
	v_mul_f64 v[34:35], v[38:39], s[74:75]
	v_fmac_f64_e32 v[26:27], s[74:75], v[38:39]
	v_mul_f64 v[38:39], v[28:29], -v[40:41]
	v_mul_f64 v[34:35], v[28:29], -v[34:35]
	v_mul_f64 v[40:41], v[38:39], s[76:77]
	v_fmac_f64_e32 v[18:19], s[76:77], v[38:39]
	v_mul_f64 v[38:39], v[34:35], s[78:79]
	v_fmac_f64_e32 v[26:27], s[78:79], v[34:35]
	v_mul_f64 v[34:35], v[28:29], -v[40:41]
	v_mul_f64 v[38:39], v[28:29], -v[38:39]
	v_mul_f64 v[40:41], v[34:35], s[30:31]
	v_fmac_f64_e32 v[18:19], s[30:31], v[34:35]
	v_mul_f64 v[34:35], v[38:39], s[82:83]
	v_fmac_f64_e32 v[26:27], s[82:83], v[38:39]
	v_mul_f64 v[38:39], v[28:29], -v[40:41]
	v_mul_f64 v[34:35], v[28:29], -v[34:35]
	v_mul_f64 v[40:41], v[38:39], s[84:85]
	v_fmac_f64_e32 v[18:19], s[84:85], v[38:39]
	v_mul_f64 v[38:39], v[34:35], s[86:87]
	v_fmac_f64_e32 v[26:27], s[86:87], v[34:35]
	v_mul_f64 v[34:35], v[28:29], -v[40:41]
	v_mul_f64 v[38:39], v[28:29], -v[38:39]
	v_mul_f64 v[40:41], v[34:35], s[88:89]
	v_fmac_f64_e32 v[18:19], s[88:89], v[34:35]
	v_mul_f64 v[34:35], v[38:39], s[90:91]
	v_fmac_f64_e32 v[26:27], s[90:91], v[38:39]
	v_mul_f64 v[38:39], v[28:29], v[40:41]
	v_mul_f64 v[28:29], v[28:29], v[34:35]
	v_mul_f64 v[36:37], v[30:31], s[38:39]
	v_fmac_f64_e32 v[26:27], s[44:45], v[28:29]
	v_mul_f64 v[28:29], v[20:21], -v[32:33]
	v_mul_f64 v[32:33], v[28:29], s[48:49]
	v_fmac_f64_e32 v[16:17], s[48:49], v[28:29]
	v_mul_f64 v[28:29], v[20:21], -v[36:37]
	v_fmac_f64_e32 v[22:23], s[38:39], v[30:31]
	v_mul_f64 v[30:31], v[28:29], s[50:51]
	v_fmac_f64_e32 v[22:23], s[50:51], v[28:29]
	v_mul_f64 v[28:29], v[20:21], -v[30:31]
	v_mul_f64 v[30:31], v[28:29], s[54:55]
	v_fmac_f64_e32 v[22:23], s[54:55], v[28:29]
	v_mul_f64 v[28:29], v[20:21], -v[30:31]
	v_mul_f64 v[30:31], v[28:29], s[58:59]
	v_fmac_f64_e32 v[22:23], s[58:59], v[28:29]
	v_mul_f64 v[28:29], v[20:21], -v[30:31]
	v_mul_f64 v[30:31], v[28:29], s[62:63]
	v_fmac_f64_e32 v[22:23], s[62:63], v[28:29]
	v_mul_f64 v[28:29], v[20:21], -v[30:31]
	v_mul_f64 v[30:31], v[28:29], s[40:41]
	v_fmac_f64_e32 v[22:23], s[40:41], v[28:29]
	v_mul_f64 v[28:29], v[20:21], -v[30:31]
	v_mul_f64 v[30:31], v[28:29], s[68:69]
	v_fmac_f64_e32 v[22:23], s[68:69], v[28:29]
	v_mul_f64 v[28:29], v[20:21], -v[30:31]
	v_mul_f64 v[30:31], v[28:29], s[72:73]
	v_fmac_f64_e32 v[22:23], s[72:73], v[28:29]
	v_mul_f64 v[28:29], v[20:21], -v[30:31]
	v_mul_f64 v[30:31], v[28:29], s[76:77]
	v_fmac_f64_e32 v[22:23], s[76:77], v[28:29]
	v_mul_f64 v[28:29], v[20:21], -v[30:31]
	v_mul_f64 v[30:31], v[28:29], s[30:31]
	v_fmac_f64_e32 v[22:23], s[30:31], v[28:29]
	v_mul_f64 v[28:29], v[20:21], -v[30:31]
	v_mul_f64 v[30:31], v[28:29], s[84:85]
	v_fmac_f64_e32 v[22:23], s[84:85], v[28:29]
	v_mul_f64 v[28:29], v[20:21], -v[30:31]
	v_mul_f64 v[32:33], v[20:21], -v[32:33]
	v_mul_f64 v[30:31], v[28:29], s[88:89]
	v_mul_f64 v[34:35], v[32:33], s[52:53]
	v_fmac_f64_e32 v[22:23], s[88:89], v[28:29]
	v_mul_f64 v[28:29], v[20:21], v[30:31]
	v_mul_f64 v[24:25], v[24:25], v[12:13]
	v_fmac_f64_e32 v[16:17], s[52:53], v[32:33]
	v_mul_f64 v[32:33], v[20:21], -v[34:35]
	v_fmac_f64_e32 v[22:23], s[92:93], v[28:29]
	v_ldexp_f64 v[28:29], v[24:25], -8
	v_mul_f64 v[34:35], v[32:33], s[56:57]
	v_fma_f64 v[30:31], v[28:29], s[8:9], 1.0
	v_fmac_f64_e32 v[16:17], s[56:57], v[32:33]
	v_mul_f64 v[32:33], v[20:21], -v[34:35]
	v_mul_f64 v[30:31], v[28:29], v[30:31]
	v_mul_f64 v[34:35], v[32:33], s[60:61]
	v_fma_f64 v[30:31], v[30:31], s[12:13], 1.0
	v_fmac_f64_e32 v[16:17], s[60:61], v[32:33]
	v_mul_f64 v[32:33], v[20:21], -v[34:35]
	v_mul_f64 v[30:31], v[28:29], v[30:31]
	v_mul_f64 v[34:35], v[32:33], s[64:65]
	v_fma_f64 v[30:31], v[30:31], s[14:15], 1.0
	v_fmac_f64_e32 v[16:17], s[64:65], v[32:33]
	v_mul_f64 v[32:33], v[20:21], -v[34:35]
	v_mul_f64 v[30:31], v[28:29], v[30:31]
	v_mul_f64 v[34:35], v[32:33], s[66:67]
	v_fma_f64 v[30:31], v[30:31], s[16:17], 1.0
	v_fmac_f64_e32 v[16:17], s[66:67], v[32:33]
	v_mul_f64 v[32:33], v[20:21], -v[34:35]
	v_mul_f64 v[30:31], v[28:29], v[30:31]
	v_mul_f64 v[34:35], v[32:33], s[4:5]
	v_fma_f64 v[30:31], v[30:31], s[18:19], 1.0
	v_fmac_f64_e32 v[16:17], s[4:5], v[32:33]
	v_mul_f64 v[32:33], v[20:21], -v[34:35]
	v_mul_f64 v[30:31], v[28:29], v[30:31]
	v_mul_f64 v[34:35], v[32:33], s[74:75]
	v_fma_f64 v[30:31], v[30:31], s[20:21], 1.0
	v_fmac_f64_e32 v[16:17], s[74:75], v[32:33]
	v_mul_f64 v[32:33], v[20:21], -v[34:35]
	v_mul_f64 v[30:31], v[28:29], v[30:31]
	v_mul_f64 v[34:35], v[32:33], s[78:79]
	v_fma_f64 v[30:31], v[30:31], s[22:23], 1.0
	v_fmac_f64_e32 v[16:17], s[78:79], v[32:33]
	v_mul_f64 v[32:33], v[20:21], -v[34:35]
	v_mul_f64 v[30:31], v[28:29], v[30:31]
	v_mul_f64 v[34:35], v[32:33], s[82:83]
	v_fma_f64 v[30:31], v[30:31], s[24:25], 1.0
	v_fmac_f64_e32 v[16:17], s[82:83], v[32:33]
	v_mul_f64 v[32:33], v[20:21], -v[34:35]
	v_mul_f64 v[30:31], v[28:29], v[30:31]
	v_mul_f64 v[34:35], v[32:33], s[86:87]
	v_fma_f64 v[30:31], v[30:31], s[26:27], 1.0
	v_ldexp_f64 v[24:25], v[24:25], 7
	v_fmac_f64_e32 v[16:17], s[86:87], v[32:33]
	v_mul_f64 v[32:33], v[20:21], -v[34:35]
	v_mul_f64 v[30:31], v[28:29], v[30:31]
	v_ldexp_f64 v[24:25], v[24:25], -8
	v_mul_f64 v[34:35], v[32:33], s[90:91]
	v_fmac_f64_e32 v[16:17], s[90:91], v[32:33]
	v_fma_f64 v[30:31], v[30:31], s[28:29], 1.0
	v_fma_f64 v[32:33], v[24:25], s[8:9], 1.0
	v_mul_f64 v[30:31], v[28:29], v[30:31]
	v_mul_f64 v[32:33], v[24:25], v[32:33]
	v_fma_f64 v[30:31], v[30:31], 0.5, 1.0
	v_fma_f64 v[32:33], v[32:33], s[12:13], 1.0
	v_fma_f64 v[28:29], v[28:29], v[30:31], 1.0
	v_mul_f64 v[32:33], v[24:25], v[32:33]
	v_mul_f64 v[28:29], v[28:29], v[28:29]
	v_fma_f64 v[32:33], v[32:33], s[14:15], 1.0
	v_mul_f64 v[28:29], v[28:29], v[28:29]
	v_mul_f64 v[32:33], v[24:25], v[32:33]
	v_mul_f64 v[28:29], v[28:29], v[28:29]
	v_fma_f64 v[32:33], v[32:33], s[16:17], 1.0
	v_mul_f64 v[28:29], v[28:29], v[28:29]
	v_mul_f64 v[32:33], v[24:25], v[32:33]
	v_mul_f64 v[28:29], v[28:29], v[28:29]
	v_fma_f64 v[32:33], v[32:33], s[18:19], 1.0
	v_mul_f64 v[28:29], v[28:29], v[28:29]
	v_mul_f64 v[32:33], v[24:25], v[32:33]
	v_mul_f64 v[28:29], v[28:29], v[28:29]
	v_fma_f64 v[32:33], v[32:33], s[20:21], 1.0
	v_fmac_f64_e32 v[18:19], s[92:93], v[38:39]
	v_mul_f64 v[28:29], v[28:29], v[28:29]
	v_mul_f64 v[32:33], v[24:25], v[32:33]
	v_mul_f64 v[30:31], v[18:19], v[28:29]
	v_fma_f64 v[32:33], v[32:33], s[22:23], 1.0
	v_mul_f64 v[32:33], v[24:25], v[32:33]
	v_cvt_f32_f64_e32 v3, v[30:31]
	s_waitcnt lgkmcnt(0)
; __device__ __forceinline__ bf16 f2bf(float f) { return (bf16)(cvt_pk_nv(f, 0.f) & 0xffffu); }
;     __device__ __forceinline__ const float* in(int i) const { return karg_in(i); }
; __device__ __forceinline__ void p0_prologue(const Ctx& C, LAS unsigned char* lds, int wave, int lane, int tid) {
;     ...
;         const double er = dexp(lr * dt), lbr = er * c1, lbi = er * s1;
;         const double e8 = dexp(lr * dt * 128.0), l8r = e8 * c8, l8i = e8 * s8;
;         C.LAM()[0 * 2048 + idx] = (float)lbr; C.LAM()[1 * 2048 + idx] = (float)lbi; C.LAM()[2 * 2048 + idx] = (float)l8r; C.LAM()[3 * 2048 + idx] = (float)l8i;
;         const double a = lbr - 1.0, b = lbi, den = lr * lr + li * li, cr = (a * lr + b * li) / den, ci = (b * lr - a * li) / den;
;         for (int n = 0; n < GN; ++n) {
;             const double br = (double)C.in(17)[(size_t)idx * GN + n], bi = (double)C.in(18)[(size_t)idx * GN + n];
;             C.BB()[((size_t)g * 128 + 2 * p) * GN + n] = f2bf((float)(cr * br - ci * bi));
;             C.BB()[((size_t)g * 128 + 2 * p + 1) * GN + n] = f2bf((float)(cr * bi + ci * br));
;             C.CM()[((size_t)g * GN + n) * 128 + 2 * p] = f2bf(C.in(19)[((size_t)g * GN + n) * NP + p]);
;             C.CM()[((size_t)g * GN + n) * 128 + 2 * p + 1] = f2bf(-C.in(20)[((size_t)g * GN + n) * NP + p]);
;         }
	v_lshl_add_u64 v[30:31], s[0:1], 0, v[8:9]
	s_mov_b32 s0, 0x2a40000
	v_fma_f64 v[32:33], v[32:33], s[24:25], 1.0
	v_add_co_u32_e32 v30, vcc, s0, v30
	v_mul_f64 v[32:33], v[24:25], v[32:33]
	s_nop 0
	v_addc_co_u32_e32 v31, vcc, 0, v31, vcc
	s_mov_b64 s[0:1], s[80:81]
	v_fma_f64 v[32:33], v[32:33], s[26:27], 1.0
	global_store_dword v[30:31], v3, off
	v_mul_f64 v[32:33], v[24:25], v[32:33]
	s_load_dwordx2 s[0:1], s[0:1], 0x110
	v_fma_f64 v[32:33], v[32:33], s[28:29], 1.0
	v_mul_f64 v[32:33], v[24:25], v[32:33]
	v_fma_f64 v[32:33], v[32:33], 0.5, 1.0
	v_fma_f64 v[24:25], v[24:25], v[32:33], 1.0
	v_mul_f64 v[24:25], v[24:25], v[24:25]
	s_waitcnt lgkmcnt(0)
	v_lshl_add_u64 v[30:31], s[0:1], 0, v[8:9]
	s_mov_b32 s0, 0x2a42000
	v_mul_f64 v[26:27], v[26:27], v[28:29]
	v_mul_f64 v[24:25], v[24:25], v[24:25]
	v_add_co_u32_e32 v30, vcc, s0, v30
	v_mul_f64 v[24:25], v[24:25], v[24:25]
	v_cvt_f32_f64_e32 v3, v[26:27]
	v_addc_co_u32_e32 v31, vcc, 0, v31, vcc
	s_mov_b64 s[0:1], s[80:81]
	v_mul_f64 v[24:25], v[24:25], v[24:25]
	global_store_dword v[30:31], v3, off
	v_mul_f64 v[24:25], v[24:25], v[24:25]
	s_load_dwordx2 s[0:1], s[0:1], 0x110
	v_mul_f64 v[24:25], v[24:25], v[24:25]
	v_mul_f64 v[24:25], v[24:25], v[24:25]
	v_mul_f64 v[24:25], v[24:25], v[24:25]
	v_mul_f64 v[22:23], v[22:23], v[24:25]
	v_cvt_f32_f64_e32 v3, v[22:23]
	s_waitcnt lgkmcnt(0)
	v_lshl_add_u64 v[22:23], s[0:1], 0, v[8:9]
	s_mov_b32 s0, 0x2a44000
	v_add_co_u32_e32 v22, vcc, s0, v22
	s_mov_b64 s[0:1], s[80:81]
	s_nop 0
	v_addc_co_u32_e32 v23, vcc, 0, v23, vcc
	global_store_dword v[22:23], v3, off
	v_mul_f64 v[20:21], v[20:21], v[34:35]
	s_load_dwordx2 s[0:1], s[0:1], 0x110
	v_fmac_f64_e32 v[16:17], s[44:45], v[20:21]
	v_mul_f64 v[16:17], v[16:17], v[24:25]
	v_cvt_f32_f64_e32 v3, v[16:17]
	v_fma_f64 v[16:17], v[18:19], v[28:29], -1.0
	v_mul_f64 v[18:19], v[14:15], v[14:15]
	v_mul_f64 v[20:21], v[16:17], v[12:13]
	v_fmac_f64_e32 v[18:19], v[12:13], v[12:13]
	v_fmac_f64_e32 v[20:21], v[26:27], v[14:15]
	s_waitcnt lgkmcnt(0)
	v_lshl_add_u64 v[8:9], s[0:1], 0, v[8:9]
	v_div_scale_f64 v[22:23], s[0:1], v[18:19], v[18:19], v[20:21]
	v_rcp_f64_e32 v[24:25], v[22:23]
	s_mov_b32 s0, 0x2a46000
	v_add_co_u32_e32 v8, vcc, s0, v8
	v_mul_f64 v[14:15], v[16:17], v[14:15]
	s_nop 0
	v_addc_co_u32_e32 v9, vcc, 0, v9, vcc
	global_store_dword v[8:9], v3, off
	v_fma_f64 v[8:9], -v[22:23], v[24:25], 1.0
	v_fmac_f64_e32 v[24:25], v[24:25], v[8:9]
	v_fma_f64 v[12:13], v[26:27], v[12:13], -v[14:15]
	v_fma_f64 v[8:9], -v[22:23], v[24:25], 1.0
	v_div_scale_f64 v[14:15], s[0:1], v[18:19], v[18:19], v[12:13]
	v_fmac_f64_e32 v[24:25], v[24:25], v[8:9]
	v_div_scale_f64 v[8:9], vcc, v[20:21], v[18:19], v[20:21]
	v_rcp_f64_e32 v[16:17], v[14:15]
	v_mul_f64 v[28:29], v[8:9], v[24:25]
	v_fma_f64 v[8:9], -v[22:23], v[28:29], v[8:9]
	s_nop 0
	v_div_fmas_f64 v[8:9], v[8:9], v[24:25], v[28:29]
	v_div_fixup_f64 v[8:9], v[8:9], v[18:19], v[20:21]
	v_fma_f64 v[20:21], -v[14:15], v[16:17], 1.0
	v_fmac_f64_e32 v[16:17], v[16:17], v[20:21]
	v_fma_f64 v[20:21], -v[14:15], v[16:17], 1.0
	v_fmac_f64_e32 v[16:17], v[16:17], v[20:21]
	v_div_scale_f64 v[20:21], vcc, v[12:13], v[18:19], v[12:13]
	v_mul_f64 v[22:23], v[20:21], v[16:17]
	v_fma_f64 v[14:15], -v[14:15], v[22:23], v[20:21]
	s_nop 1
	v_div_fmas_f64 v[14:15], v[14:15], v[16:17], v[22:23]
	v_lshlrev_b32_e32 v16, 1, v10
	v_ashrrev_i32_e32 v17, 31, v16
	v_div_fixup_f64 v[12:13], v[14:15], v[18:19], v[12:13]
	v_lshlrev_b64 v[14:15], 5, v[16:17]
	v_lshlrev_b64 v[16:17], 1, v[16:17]
	v_lshlrev_b64 v[10:11], 2, v[10:11]
	v_and_b32_e32 v42, 15, v84
	v_mov_b32_e32 v43, 0
	v_lshl_add_u64 v[4:5], v[42:43], 2, v[4:5]
	v_lshl_add_u64 v[14:15], v[42:43], 1, v[14:15]
	v_lshlrev_b32_e32 v44, 8, v42
	v_mov_b32_e32 v45, 0
	v_lshl_add_u64 v[10:11], v[44:45], 0, v[10:11]
	v_lshl_add_u64 v[16:17], v[44:45], 0, v[16:17]
	v_and_b32_e32 v49, 63, v2
	v_bfe_u32 v50, v49, 5, 1
	v_lshlrev_b32_e32 v50, 11, v50
	v_and_b32_e32 v51, 31, v49
	v_lshl_or_b32 v50, v51, 4, v50
	v_bfe_u32 v51, v42, 3, 1
	v_lshl_or_b32 v50, v51, 9, v50
	v_and_b32_e32 v51, 7, v42
	v_lshl_or_b32 v50, v51, 1, v50
	v_add_u32_e32 v50, 0x2a48000, v50
	v_mov_b32_e32 v51, 0
	v_lshrrev_b32_e32 v56, 4, v49
	v_lshlrev_b32_e32 v56, 10, v56
	v_bfe_u32 v57, v49, 2, 2
	v_lshl_or_b32 v56, v57, 8, v56
	v_lshl_or_b32 v56, v42, 4, v56
	v_and_b32_e32 v57, 3, v49
	v_lshl_or_b32 v56, v57, 2, v56
	v_add_u32_e32 v56, 0x2aa1000, v56
	v_mov_b32_e32 v57, 0
; __device__ __forceinline__ bf16 f2bf(float f) { return (bf16)(cvt_pk_nv(f, 0.f) & 0xffffu); }
;     __device__ __forceinline__ const float* in(int i) const { return karg_in(i); }
; __device__ __forceinline__ void p0_prologue(const Ctx& C, LAS unsigned char* lds, int wave, int lane, int tid) {
;     ...
;         for (int n = 0; n < GN; ++n) {
;             const double br = (double)C.in(17)[(size_t)idx * GN + n], bi = (double)C.in(18)[(size_t)idx * GN + n];
;             C.BB()[((size_t)g * 128 + 2 * p) * GN + n] = f2bf((float)(cr * br - ci * bi));
;             C.BB()[((size_t)g * 128 + 2 * p + 1) * GN + n] = f2bf((float)(cr * bi + ci * br));
;             C.CM()[((size_t)g * GN + n) * 128 + 2 * p] = f2bf(C.in(19)[((size_t)g * GN + n) * NP + p]);
;             C.CM()[((size_t)g * GN + n) * 128 + 2 * p + 1] = f2bf(-C.in(20)[((size_t)g * GN + n) * NP + p]);
;         }
.LBB0_127:
	s_mov_b64 s[0:1], s[80:81]
	s_load_dwordx2 s[0:1], s[0:1], 0x88
	s_mov_b64 s[70:71], s[80:81]
	s_mov_b64 s[94:95], s[80:81]
	s_waitcnt lgkmcnt(0)
	v_lshl_add_u64 v[18:19], s[0:1], 0, v[4:5]
	v_lshl_add_u64 v[18:19], v[18:19], 0, s[42:43]
	global_load_dword v3, v[18:19], off
	s_load_dwordx2 s[0:1], s[70:71], 0x90
	s_mov_b64 s[70:71], s[80:81]
	s_waitcnt lgkmcnt(0)
	v_lshl_add_u64 v[18:19], s[0:1], 0, v[4:5]
	v_lshl_add_u64 v[18:19], v[18:19], 0, s[42:43]
	global_load_dword v22, v[18:19], off
	s_mov_b64 s[0:1], s[80:81]
	s_load_dwordx2 s[0:1], s[0:1], 0x110
	s_add_u32 s42, s42, 4
	s_addc_u32 s43, s43, 0
	s_cmp_eq_u32 s42, 64
	s_waitcnt lgkmcnt(0)
	v_lshl_add_u64 v[18:19], s[0:1], 0, v[6:7]
	v_lshl_add_u64 v[52:53], v[18:19], 0, v[50:51]
	v_lshl_add_u64 v[18:19], v[18:19], 0, v[14:15]
	v_add_co_u32_e32 v18, vcc, s47, v18
	s_waitcnt vmcnt(1)
	v_cvt_f64_f32_e32 v[20:21], v3
	v_addc_co_u32_e32 v19, vcc, 0, v19, vcc
	s_waitcnt vmcnt(0)
	v_cvt_f64_f32_e32 v[22:23], v22
	v_mul_f64 v[24:25], v[12:13], v[22:23]
	v_fma_f64 v[24:25], v[8:9], v[20:21], -v[24:25]
	v_cvt_f32_f64_e32 v3, v[24:25]
	v_cvt_pk_bf16_f32 v3, v3, v1
	global_store_short v[18:19], v3, off
	global_store_short v[52:53], v3, off
	s_load_dwordx2 s[0:1], s[70:71], 0x110
	v_mul_f64 v[22:23], v[8:9], v[22:23]
	v_fmac_f64_e32 v[22:23], v[12:13], v[20:21]
	v_cvt_f32_f64_e32 v20, v[22:23]
	v_cvt_pk_bf16_f32 v20, v20, v1
	s_waitcnt lgkmcnt(0)
	v_lshl_add_u64 v[18:19], s[0:1], 0, v[6:7]
	v_lshl_add_u64 v[18:19], v[18:19], 0, v[14:15]
	v_add_co_u32_e32 v18, vcc, s47, v18
	s_mov_b64 s[70:71], s[80:81]
	s_nop 0
	v_addc_co_u32_e32 v19, vcc, 0, v19, vcc
	global_store_short v[18:19], v20, off offset:32
	global_store_short v[52:53], v20, off offset:1024
	s_load_dwordx2 s[0:1], s[94:95], 0x98
	v_lshl_add_u64 v[14:15], v[14:15], 0, 2
	s_waitcnt lgkmcnt(0)
	v_lshl_add_u64 v[18:19], s[0:1], 0, v[6:7]
	v_lshl_add_u64 v[18:19], v[18:19], 0, v[10:11]
	s_mov_b64 s[0:1], s[80:81]
	global_load_dword v3, v[18:19], off
	s_load_dwordx2 s[0:1], s[0:1], 0x110
	s_waitcnt vmcnt(0)
	v_cvt_pk_bf16_f32 v3, v3, v1
	s_waitcnt lgkmcnt(0)
	v_lshl_add_u64 v[18:19], s[0:1], 0, v[6:7]
	v_lshl_add_u64 v[54:55], v[18:19], 0, v[56:57]
	v_lshl_add_u64 v[18:19], v[18:19], 0, v[16:17]
	v_add_co_u32_e32 v18, vcc, s10, v18
	s_nop 1
	v_addc_co_u32_e32 v19, vcc, 0, v19, vcc
	global_store_short v[18:19], v3, off
	global_store_short v[54:55], v3, off
	s_load_dwordx2 s[0:1], s[70:71], 0xa0
	s_waitcnt lgkmcnt(0)
	v_lshl_add_u64 v[18:19], s[0:1], 0, v[6:7]
	v_lshl_add_u64 v[18:19], v[18:19], 0, v[10:11]
	global_load_dword v3, v[18:19], off
	s_mov_b64 s[0:1], s[80:81]
	s_load_dwordx2 s[0:1], s[0:1], 0x110
	v_lshl_add_u64 v[10:11], v[10:11], 0, s[96:97]
	s_waitcnt lgkmcnt(0)
	v_lshl_add_u64 v[18:19], s[0:1], 0, v[6:7]
	v_lshl_add_u64 v[18:19], v[18:19], 0, v[16:17]
	v_add_co_u32_e32 v18, vcc, s10, v18
	v_lshl_add_u64 v[16:17], v[16:17], 0, s[96:97]
	s_nop 0
	v_addc_co_u32_e32 v19, vcc, 0, v19, vcc
	s_waitcnt vmcnt(0)
	v_xor_b32_e32 v3, 0x80000000, v3
	v_cvt_pk_bf16_f32 v3, v3, v1
	global_store_short v[18:19], v3, off offset:2
	global_store_short v[54:55], v3, off offset:2
	v_add_u32_e32 v2, s46, v2
	s_movk_i32 s0, 0x7ff
	v_cmp_lt_i32_e32 vcc, s0, v2
	s_or_b64 s[6:7], vcc, s[6:7]
	s_andn2_b64 exec, exec, s[6:7]
	s_cbranch_execnz .LBB0_126

; #define LAS __attribute__((address_space(3)))
;     __device__ __forceinline__ const float* in(int i) const { return karg_in(i); }
; template <bool PASS2>
; __device__ __forceinline__ void s5_tile(const Ctx& C, int T, int sb_lo, int sb_hi, LAS unsigned char* lds, int wave, int lane) {
;     ...
;     LAS bf16* XU = (LAS bf16*)(lds + wave * S5W_BYTES);
;     LAS bf16* BH = XU + 32 * XU_STRIDE;
;     const int tl = lane & 31, hh = lane >> 5, fr = lane & 15, kq = lane >> 4, xrow = lane >> 3, xpart = lane & 7;
;     const float* LAM = C.LAM();
;     const bf16* Zb = C.Z() + (size_t)1024 + 64 * wave;
;     float sr[4], si[4], lr[4], li[4], dsk[4];
; #pragma unroll
;     for (int gi = 0; gi < 4; ++gi) { const int g = wave * 4 + gi; sr[gi] = 0.f; si[gi] = 0.f; lr[gi] = LAM[0 * 2048 + g * 64 + lane]; li[gi] = LAM[1 * 2048 + g * 64 + lane];
;         dsk[gi] = PASS2 ? C.in(21)[16 * g + fr] : 0.f; }
;     if (PASS2 && !sample) {
;         const int k = T & 127, tb = T - k;
;         float l8r[4], l8i[4];
; #pragma unroll
;         for (int gi = 0; gi < 4; ++gi) { l8r[gi] = LAM[2 * 2048 + (wave * 4 + gi) * 64 + lane]; l8i[gi] = LAM[3 * 2048 + (wave * 4 + gi) * 64 + lane]; }
;         const v2f* Ep = (const v2f*)C.E() + ((size_t)tb * NG + wave * 4) * NP + lane;
;         const int nb = (k + 15) >> 4, j0 = k - 16 * nb;
;         for (int jb = 0; jb < nb; ++jb) {
; #pragma unroll
;             for (int u = 0; u < 16; ++u) {
;                 const int j = j0 + 16 * jb + u; const bool ok = j >= 0; const int jc = ok ? j : 0;
; #pragma unroll
;                 for (int gi = 0; gi < 4; ++gi) { v2f e = Ep[(size_t)jc * NG * NP + gi * NP]; if (!ok) e = (v2f){0.f, 0.f};
;                     const float nr = fmaf(l8r[gi], sr[gi], fmaf(-l8i[gi], si[gi], e.x)), ni = fmaf(l8r[gi], si[gi], fmaf(l8i[gi], sr[gi], e.y)); sr[gi] = nr; si[gi] = ni; }
;             }
;         }
;     }
;     v4u xn[4];
;     {
;         const int sb0 = sb_lo;
; #pragma unroll
;         for (int i = 0; i < 4; ++i) xn[i] = *(const v4u*)(Zb + (size_t)(r0 + 32 * sb0 + xrow + 8 * i) * DIN + 8 * xpart);
;     }
;     const bf16* BBt = C.BB(); const bf16* CMt = C.CM();
;     bfx8 bbn[4], cmn[4];
; #pragma unroll
;     for (int cb = 0; cb < 4; ++cb) bbn[cb] = *(const bfx8*)(BBt + ((size_t)(wave * 4 * 128 + cb * 32 + tl)) * GN + 8 * hh);
.LBB0_595:
	s_mov_b64 s[0:1], s[80:81]
	s_load_dwordx2 s[0:1], s[0:1], 0x110
	v_readfirstlane_b32 s13, v81
	s_ashr_i32 s42, s13, 6
	s_mul_i32 s3, s42, 0x3400
	s_add_i32 s3, s3, 0
	s_waitcnt lgkmcnt(0)
	s_add_u32 s0, s0, 0x2a40000
	s_addc_u32 s1, s1, 0
	s_lshl_b32 s25, s42, 8
	s_mov_b64 s[26:27], s[80:81]
	v_add_u32_e32 v2, s25, v89
	v_ashrrev_i32_e32 v3, 31, v2
	s_load_dwordx2 s[28:29], s[26:27], 0x110
	v_lshl_add_u64 v[2:3], v[2:3], 2, s[0:1]
	s_or_b32 s26, s25, 64
	v_or_b32_e32 v0, s25, v80
	global_load_dword v65, v[2:3], off
	v_or_b32_e32 v2, s26, v80
	v_add_u32_e32 v4, s26, v89
	s_or_b32 s26, s25, 0x80
	s_or_b32 s25, s25, 0xc0
	s_and_b32 s52, s13, 0xffffffc0
	v_or_b32_e32 v6, s26, v80
	v_add_u32_e32 v8, s26, v89
	v_or_b32_e32 v10, s25, v80
	v_add_u32_e32 v12, s25, v89
	s_ashr_i32 s53, s52, 31
	v_ashrrev_i32_e32 v1, 31, v0
	v_ashrrev_i32_e32 v3, 31, v2
	v_ashrrev_i32_e32 v5, 31, v4
	v_ashrrev_i32_e32 v7, 31, v6
	v_ashrrev_i32_e32 v9, 31, v8
	v_ashrrev_i32_e32 v11, 31, v10
	v_ashrrev_i32_e32 v13, 31, v12
	v_lshl_add_u64 v[0:1], v[0:1], 2, s[0:1]
	v_lshl_add_u64 v[2:3], v[2:3], 2, s[0:1]
	v_lshl_add_u64 v[4:5], v[4:5], 2, s[0:1]
	v_lshl_add_u64 v[6:7], v[6:7], 2, s[0:1]
	v_lshl_add_u64 v[8:9], v[8:9], 2, s[0:1]
	v_lshl_add_u64 v[10:11], v[10:11], 2, s[0:1]
	v_lshl_add_u64 v[12:13], v[12:13], 2, s[0:1]
	s_lshl_b32 s26, s24, 7
	s_lshl_b64 s[0:1], s[52:53], 1
	s_waitcnt lgkmcnt(0)
	s_add_u32 s0, s28, s0
	s_addc_u32 s1, s29, s1
	global_load_dword v66, v[0:1], off
	global_load_dword v68, v[2:3], off
	global_load_dword v71, v[4:5], off
	global_load_dword v72, v[6:7], off
	global_load_dword v75, v[8:9], off
	global_load_dword v76, v[10:11], off
	global_load_dword v79, v[12:13], off
	v_or_b32_e32 v4, s26, v87
	v_lshl_add_u64 v[0:1], s[0:1], 0, v[94:95]
	v_lshl_add_u64 v[102:103], v[0:1], 0, s[14:15]
	v_or_b32_e32 v2, 8, v4
	v_mad_i64_i32 v[0:1], s[0:1], v4, s34, v[102:103]
	v_mad_i64_i32 v[2:3], s[0:1], v2, s34, v[102:103]
	global_load_dwordx4 v[16:19], v[0:1], off
	global_load_dwordx4 v[20:23], v[2:3], off
	v_or_b32_e32 v0, 16, v4
	v_or_b32_e32 v2, 24, v4
	v_mad_i64_i32 v[0:1], s[0:1], v0, s34, v[102:103]
	v_mad_i64_i32 v[2:3], s[0:1], v2, s34, v[102:103]
	s_mov_b64 s[0:1], s[80:81]
	global_load_dwordx4 v[24:27], v[0:1], off
	global_load_dwordx4 v[28:31], v[2:3], off
	s_load_dwordx2 s[0:1], s[0:1], 0x110
	v_bfe_u32 v4, v81, 1, 5
	v_lshl_or_b32 v0, s42, 9, v4
	v_ashrrev_i32_e32 v1, 31, v0
	v_lshlrev_b64 v[4:5], 5, v[0:1]
	s_mov_b64 s[28:29], s[80:81]
	s_waitcnt lgkmcnt(0)
	v_and_b32_e32 v2, 1, v81
	v_lshlrev_b32_e32 v2, 4, v2
	v_add_u32_e32 v2, 0x48000, v2
	v_mov_b32_e32 v3, 0
	v_lshl_add_u64 v[2:3], s[0:1], 0, v[2:3]
	v_lshl_add_u64 v[2:3], v[2:3], 0, s[16:17]
	v_lshl_add_u64 v[104:105], v[2:3], 0, v[4:5]
	v_or_b32_e32 v4, 32, v0
	v_ashrrev_i32_e32 v5, 31, v4
	v_lshlrev_b64 v[4:5], 5, v[4:5]
	v_lshl_add_u64 v[106:107], v[2:3], 0, v[4:5]
	v_or_b32_e32 v4, 64, v0
	v_ashrrev_i32_e32 v5, 31, v4
	v_lshlrev_b64 v[4:5], 5, v[4:5]
	v_lshl_add_u64 v[108:109], v[2:3], 0, v[4:5]
	v_or_b32_e32 v4, 0x60, v0
	v_ashrrev_i32_e32 v5, 31, v4
	v_lshlrev_b64 v[4:5], 5, v[4:5]
	global_load_dwordx4 v[44:47], v[104:105], off
	global_load_dwordx4 v[40:43], v[106:107], off
	v_lshl_add_u64 v[110:111], v[2:3], 0, v[4:5]
	global_load_dwordx4 v[36:39], v[108:109], off
	global_load_dwordx4 v[32:35], v[110:111], off
	v_or_b32_e32 v4, 0x80, v0
	v_ashrrev_i32_e32 v5, 31, v4
	v_lshlrev_b64 v[4:5], 5, v[4:5]
	v_lshl_add_u64 v[112:113], v[2:3], 0, v[4:5]
	v_or_b32_e32 v4, 0xa0, v0
	v_ashrrev_i32_e32 v5, 31, v4
	v_lshlrev_b64 v[4:5], 5, v[4:5]
	v_lshl_add_u64 v[114:115], v[2:3], 0, v[4:5]
	v_or_b32_e32 v4, 0xc0, v0
	v_ashrrev_i32_e32 v5, 31, v4
	v_lshlrev_b64 v[4:5], 5, v[4:5]
	v_lshl_add_u64 v[116:117], v[2:3], 0, v[4:5]
	v_or_b32_e32 v4, 0xe0, v0
	v_ashrrev_i32_e32 v5, 31, v4
	v_lshlrev_b64 v[4:5], 5, v[4:5]
	v_lshl_add_u64 v[118:119], v[2:3], 0, v[4:5]
	v_or_b32_e32 v4, 0x100, v0
	v_ashrrev_i32_e32 v5, 31, v4
	v_lshlrev_b64 v[4:5], 5, v[4:5]
	v_lshl_add_u64 v[120:121], v[2:3], 0, v[4:5]
	v_or_b32_e32 v4, 0x120, v0
	v_ashrrev_i32_e32 v5, 31, v4
	v_lshlrev_b64 v[4:5], 5, v[4:5]
	v_lshl_add_u64 v[122:123], v[2:3], 0, v[4:5]
	v_or_b32_e32 v4, 0x140, v0
	v_ashrrev_i32_e32 v5, 31, v4
	v_lshlrev_b64 v[4:5], 5, v[4:5]
	v_lshl_add_u64 v[124:125], v[2:3], 0, v[4:5]
	v_or_b32_e32 v4, 0x160, v0
	v_ashrrev_i32_e32 v5, 31, v4
	v_lshlrev_b64 v[4:5], 5, v[4:5]
	v_lshl_add_u64 v[126:127], v[2:3], 0, v[4:5]
	v_or_b32_e32 v4, 0x180, v0
	v_ashrrev_i32_e32 v5, 31, v4
	v_lshlrev_b64 v[4:5], 5, v[4:5]
	v_lshl_add_u64 v[128:129], v[2:3], 0, v[4:5]
	v_or_b32_e32 v4, 0x1a0, v0
	v_ashrrev_i32_e32 v5, 31, v4
	v_lshlrev_b64 v[4:5], 5, v[4:5]
	v_lshl_add_u64 v[130:131], v[2:3], 0, v[4:5]
	v_or_b32_e32 v4, 0x1c0, v0
	v_or_b32_e32 v0, 0x1e0, v0
	s_waitcnt vmcnt(15)
	v_xor_b32_e32 v64, 0x80000000, v65
	s_waitcnt vmcnt(12)
	v_xor_b32_e32 v70, 0x80000000, v71
	v_ashrrev_i32_e32 v5, 31, v4
	v_ashrrev_i32_e32 v1, 31, v0
	s_waitcnt vmcnt(10)
	v_xor_b32_e32 v74, 0x80000000, v75
	s_waitcnt vmcnt(8)
	v_xor_b32_e32 v78, 0x80000000, v79
	v_add_u32_e32 v6, s3, v91
	v_add_u32_e32 v7, s3, v168
	v_add_u32_e32 v8, s3, v170
	v_lshlrev_b64 v[4:5], 5, v[4:5]
	v_lshlrev_b64 v[0:1], 5, v[0:1]
	v_mov_b32_e32 v144, v65
	v_mov_b32_e32 v145, v64
	v_mov_b32_e32 v148, v71
	v_mov_b32_e32 v149, v70
	v_mov_b32_e32 v152, v75
	v_mov_b32_e32 v153, v74
	v_mov_b32_e32 v156, v79
	v_mov_b32_e32 v157, v78
	v_add_u32_e32 v82, s3, v171
	v_lshl_add_u64 v[132:133], v[2:3], 0, v[4:5]
	v_lshl_add_u64 v[134:135], v[2:3], 0, v[0:1]
	v_mov_b32_e32 v67, v66
	v_pk_mov_b32 v[136:137], v[64:65], v[64:65] op_sel:[1,0]
	v_mov_b32_e32 v69, v68
	v_pk_mov_b32 v[138:139], v[70:71], v[70:71] op_sel:[1,0]
	v_mov_b32_e32 v73, v72
	v_pk_mov_b32 v[140:141], v[74:75], v[74:75] op_sel:[1,0]
	v_mov_b32_e32 v77, v76
	v_pk_mov_b32 v[142:143], v[78:79], v[78:79] op_sel:[1,0]
	v_pk_mov_b32 v[146:147], v[144:145], v[144:145] op_sel:[1,0]
	v_pk_mov_b32 v[150:151], v[148:149], v[148:149] op_sel:[1,0]
	v_pk_mov_b32 v[154:155], v[152:153], v[152:153] op_sel:[1,0]
	v_pk_mov_b32 v[158:159], v[156:157], v[156:157] op_sel:[1,0]
	v_add_u32_e32 v97, v6, v172
	v_add_u32_e32 v101, v7, v169
	v_add_u32_e32 v178, v8, v84
	s_mov_b32 s25, 0
	v_mov_b32_e32 v166, 0
	v_mov_b32_e32 v167, v83
	v_mov_b32_e32 v164, 0
	v_mov_b32_e32 v165, v83
	v_mov_b32_e32 v162, 0
	v_mov_b32_e32 v163, v83
	v_mov_b32_e32 v160, 0
	v_mov_b32_e32 v161, v83
	s_branch .LBB0_597

; template <bool PASS2>
; __device__ __forceinline__ void s5_tile(const Ctx& C, int T, int sb_lo, int sb_hi, LAS unsigned char* lds, int wave, int lane) {
;     ...
;     const bf16* BBt = C.BB(); const bf16* CMt = C.CM();
;     bfx8 bbn[4], cmn[4];
; #pragma unroll
;     for (int cb = 0; cb < 4; ++cb) bbn[cb] = *(const bfx8*)(BBt + ((size_t)(wave * 4 * 128 + cb * 32 + tl)) * GN + 8 * hh);
;     if (PASS2) {
; #pragma unroll
;         for (int ks = 0; ks < 4; ++ks) cmn[ks] = *(const bfx8*)(CMt + ((size_t)(wave * 4 * GN + fr)) * 128 + 32 * ks + 8 * kq);
;     }
.LBB0_656:
	s_or_b64 exec, exec, s[8:9]
	v_mov_b32_e32 v160, v182
	s_cmpk_gt_i32 s94, 0x80
	s_waitcnt lgkmcnt(0)
	v_cndmask_b32_e64 v0, 0, 1, s[10:11]
	s_barrier
	s_cselect_b64 s[52:53], -1, 0
	v_cmp_ne_u32_e64 s[8:9], 1, v0
	s_andn2_b64 vcc, exec, s[10:11]
	v_bfe_u32 v162, v160, 3, 3
	v_bfe_u32 v161, v160, 4, 2
	v_and_b32_e32 v96, 48, v160
	s_cbranch_vccnz .LBB0_673
	v_and_b32_e32 v98, 63, v160
	v_and_b32_e32 v97, 31, v160
	v_and_b32_e32 v99, 15, v160
	v_bfe_u32 v1, v160, 5, 1
	v_and_b32_e32 v2, 7, v160
	v_lshlrev_b32_e32 v0, 3, v161
	v_or_b32_e32 v103, 0x800, v98
	v_or_b32_e32 v105, 0x1000, v98
	v_or_b32_e32 v163, 0x1800, v98
	v_mov_b32_e32 v101, 0
	v_lshlrev_b32_e32 v102, 3, v2
	v_lshlrev_b32_e32 v104, 3, v1
	v_lshlrev_b32_e32 v164, 4, v2
	v_mul_u32_u24_e32 v165, 0x90, v97
	v_lshlrev_b32_e32 v166, 4, v1
	v_mul_u32_u24_e32 v167, 0x110, v97
	v_lshlrev_b32_e32 v168, 2, v98
	v_mul_u32_u24_e32 v169, 0x90, v162
	v_mul_u32_u24_e32 v170, 0x240, v161
	v_mul_u32_u24_e32 v171, 0x110, v99
	v_lshl_or_b32 v172, s33, 7, v162
	s_lshl_b32 s42, s94, 7
	s_mov_b32 s55, 0
	s_mov_b64 s[56:57], 0x2b00000
	s_mov_b64 s[58:59], 0xb200800
	s_movk_i32 s43, 0xc00
	s_mov_b64 s[60:61], 0x2a00000
	v_mul_i32_i24_e32 v106, 0xffffff00, v99
	v_lshl_add_u32 v106, v98, 4, v106
	s_mov_b32 s47, 0x11300000
	s_mov_b32 s74, 0x8080000
	s_mov_b32 s75, 0x8084000
	s_mov_b32 s76, s33
	s_mov_b32 s98, 0
	s_mov_b32 s77, s33
	s_branch .LBB0_659

; template <bool PASS2>
; __device__ __forceinline__ void s5_tile(const Ctx& C, int T, int sb_lo, int sb_hi, LAS unsigned char* lds, int wave, int lane) {
;     ...
;     v4u xn[4];
;     {
;         const int sb0 = sb_lo;
; #pragma unroll
;         for (int i = 0; i < 4; ++i) xn[i] = *(const v4u*)(Zb + (size_t)(r0 + 32 * sb0 + xrow + 8 * i) * DIN + 8 * xpart);
;     }
;     const bf16* BBt = C.BB(); const bf16* CMt = C.CM();
;     bfx8 bbn[4], cmn[4];
; #pragma unroll
;     for (int cb = 0; cb < 4; ++cb) bbn[cb] = *(const bfx8*)(BBt + ((size_t)(wave * 4 * 128 + cb * 32 + tl)) * GN + 8 * hh);
;     if (PASS2) {
; #pragma unroll
;         for (int ks = 0; ks < 4; ++ks) cmn[ks] = *(const bfx8*)(CMt + ((size_t)(wave * 4 * GN + fr)) * 128 + 32 * ks + 8 * kq);
;     }
.LBB0_665:
	s_load_dwordx2 s[12:13], s[0:1], 0x110
	s_mul_i32 s0, s67, 0x3400
	s_ashr_i32 s73, s72, 31
	s_add_i32 s3, s0, 0
	s_lshl_b64 s[10:11], s[72:73], 1
	s_waitcnt lgkmcnt(0)
	s_add_u32 s0, s12, s10
	s_addc_u32 s1, s13, s11
	v_lshlrev_b32_e32 v100, 1, v102
	s_waitcnt vmcnt(3)
	v_lshl_or_b32 v12, s77, 7, v162
	v_lshl_add_u64 v[8:9], s[0:1], 0, v[100:101]
	v_lshl_add_u64 v[116:117], v[8:9], 0, s[58:59]
	v_or_b32_e32 v10, 8, v12
	v_mad_i64_i32 v[8:9], s[0:1], v12, s43, v[116:117]
	v_mad_i64_i32 v[10:11], s[0:1], v10, s43, v[116:117]
	global_load_dwordx4 v[16:19], v[8:9], off
	global_load_dwordx4 v[20:23], v[10:11], off
	v_or_b32_e32 v8, 16, v12
	v_or_b32_e32 v10, 24, v12
	v_mad_i64_i32 v[8:9], s[0:1], v8, s43, v[116:117]
	v_mad_i64_i32 v[10:11], s[0:1], v10, s43, v[116:117]
	s_mov_b64 s[0:1], s[80:81]
	global_load_dwordx4 v[24:27], v[8:9], off
	global_load_dwordx4 v[28:31], v[10:11], off
	s_mov_b64 s[12:13], s[80:81]
	s_load_dwordx2 s[0:1], s[0:1], 0x110
	s_load_dwordx2 s[12:13], s[12:13], 0x110
	v_and_b32_e32 v8, 1, v160
	v_lshlrev_b32_e32 v8, 4, v8
	v_add_u32_e32 v8, 0x48000, v8
	v_mov_b32_e32 v9, v101
	s_waitcnt lgkmcnt(0)
	v_lshl_add_u64 v[8:9], s[0:1], 0, v[8:9]
	v_lshlrev_b64 v[6:7], 8, v[6:7]
	s_add_u32 s0, s12, 0x2aa1000
	s_addc_u32 s1, s13, 0
	v_lshl_add_u64 v[10:11], s[0:1], 0, v[6:7]
	v_ashrrev_i32_e32 v107, 31, v106
	v_lshl_add_u64 v[10:11], v[10:11], 0, v[106:107]
	global_load_dwordx4 v[32:35], v[10:11], off offset:3072
	global_load_dwordx4 v[36:39], v[10:11], off offset:2048
	global_load_dwordx4 v[40:43], v[10:11], off offset:1024
	global_load_dwordx4 v[44:47], v[10:11], off
	v_bfe_u32 v231, v160, 1, 5
	v_lshl_or_b32 v10, s67, 9, v231
	v_or_b32_e32 v12, 0x60, v10
	s_waitcnt vmcnt(9)
	v_ashrrev_i32_e32 v13, 31, v12
	v_lshl_add_u64 v[8:9], v[8:9], 0, s[60:61]
	v_lshlrev_b64 v[12:13], 5, v[12:13]
	v_lshl_add_u64 v[118:119], v[8:9], 0, v[12:13]
	v_or_b32_e32 v12, 64, v10
	v_ashrrev_i32_e32 v13, 31, v12
	v_lshlrev_b64 v[12:13], 5, v[12:13]
	v_lshl_add_u64 v[120:121], v[8:9], 0, v[12:13]
	v_or_b32_e32 v12, 32, v10
	v_ashrrev_i32_e32 v13, 31, v12
	v_lshlrev_b64 v[12:13], 5, v[12:13]
	v_ashrrev_i32_e32 v11, 31, v10
	v_lshl_add_u64 v[122:123], v[8:9], 0, v[12:13]
	v_lshlrev_b64 v[10:11], 5, v[10:11]
	global_load_dwordx4 v[64:67], v[118:119], off
	global_load_dwordx4 v[68:71], v[120:121], off
	v_lshl_add_u64 v[124:125], v[8:9], 0, v[10:11]
	global_load_dwordx4 v[72:75], v[122:123], off
	global_load_dwordx4 v[76:79], v[124:125], off
	v_lshl_or_b32 v12, s64, 7, v231
	v_ashrrev_i32_e32 v13, 31, v12
	s_waitcnt vmcnt(12)
	v_lshlrev_b64 v[14:15], 5, v[12:13]
	v_lshl_add_u64 v[126:127], v[8:9], 0, v[14:15]
	v_or_b32_e32 v14, 32, v12
	v_ashrrev_i32_e32 v15, 31, v14
	v_lshlrev_b64 v[14:15], 5, v[14:15]
	v_lshl_add_u64 v[10:11], s[0:1], 0, v[106:107]
	v_lshl_add_u64 v[128:129], v[8:9], 0, v[14:15]
	v_or_b32_e32 v14, 64, v12
	v_or_b32_e32 v12, 0x60, v12
	v_lshlrev_b64 v[4:5], 8, v[4:5]
	v_ashrrev_i32_e32 v13, 31, v12
	v_lshl_add_u64 v[134:135], v[10:11], 0, v[4:5]
	v_lshl_or_b32 v4, s66, 7, v231
	v_lshlrev_b64 v[12:13], 5, v[12:13]
	v_ashrrev_i32_e32 v5, 31, v4
	v_lshl_add_u64 v[132:133], v[8:9], 0, v[12:13]
	v_lshlrev_b64 v[12:13], 5, v[4:5]
	v_lshl_add_u64 v[136:137], v[8:9], 0, v[12:13]
	v_or_b32_e32 v12, 32, v4
	v_ashrrev_i32_e32 v13, 31, v12
	v_lshlrev_b64 v[12:13], 5, v[12:13]
	v_lshl_add_u64 v[138:139], v[8:9], 0, v[12:13]
	v_or_b32_e32 v12, 64, v4
	v_or_b32_e32 v4, 0x60, v4
	v_lshlrev_b64 v[2:3], 8, v[2:3]
	v_ashrrev_i32_e32 v5, 31, v4
	v_lshl_add_u64 v[144:145], v[10:11], 0, v[2:3]
	v_lshl_or_b32 v2, s68, 7, v231
	v_lshlrev_b64 v[4:5], 5, v[4:5]
	v_ashrrev_i32_e32 v3, 31, v2
	v_lshl_add_u64 v[142:143], v[8:9], 0, v[4:5]
	v_lshlrev_b64 v[4:5], 5, v[2:3]
	v_lshl_add_u64 v[146:147], v[8:9], 0, v[4:5]
	v_or_b32_e32 v4, 32, v2
	v_ashrrev_i32_e32 v5, 31, v4
	v_lshlrev_b64 v[4:5], 5, v[4:5]
	v_lshl_add_u64 v[148:149], v[8:9], 0, v[4:5]
	v_or_b32_e32 v4, 64, v2
	v_or_b32_e32 v2, 0x60, v2
	v_ashrrev_i32_e32 v15, 31, v14
	v_ashrrev_i32_e32 v13, 31, v12
	v_ashrrev_i32_e32 v5, 31, v4
	v_ashrrev_i32_e32 v3, 31, v2
	v_add_u32_e32 v48, s3, v164
	v_lshl_add_u32 v49, v99, 1, s3
	v_add_u32_e32 v50, s3, v165
	v_add_u32_e32 v51, s3, v167
	v_add_u32_e32 v52, s3, v96
	v_lshlrev_b64 v[14:15], 5, v[14:15]
	v_lshlrev_b64 v[12:13], 5, v[12:13]
	v_lshlrev_b64 v[4:5], 5, v[4:5]
	v_lshlrev_b64 v[2:3], 5, v[2:3]
	v_lshlrev_b64 v[0:1], 8, v[0:1]
	v_add_u32_e32 v107, s3, v168
	v_lshl_add_u64 v[130:131], v[8:9], 0, v[14:15]
	v_lshl_add_u64 v[140:141], v[8:9], 0, v[12:13]
	v_lshl_add_u64 v[150:151], v[8:9], 0, v[4:5]
	v_lshl_add_u64 v[152:153], v[8:9], 0, v[2:3]
	v_lshl_add_u64 v[154:155], v[10:11], 0, v[0:1]
	v_lshl_add_u64 v[156:157], v[10:11], 0, v[6:7]
	s_mov_b32 s14, 0
	v_add_u32_e32 v192, v50, v166
	v_add_u32_e32 v193, v51, v104
	v_add_u32_e32 v194, v52, v171
	v_add_u32_e32 v195, v49, v170
	v_add_u32_e32 v196, v48, v169
	s_mov_b32 s15, 0
	s_branch .LBB0_667
; #define LAS __attribute__((address_space(3)))
; template <bool PASS2>
; __device__ __forceinline__ void s5_tile(const Ctx& C, int T, int sb_lo, int sb_hi, LAS unsigned char* lds, int wave, int lane) {
;     ...
;         for (int gi = 0; gi < 4; ++gi) {
;             const int g = wave * 4 + gi, gnx = wave * 4 + ((gi + 1) & 3);
;             bfx8 bb[4], cm[4];
; #pragma unroll
;             for (int cb = 0; cb < 4; ++cb) { bb[cb] = bbn[cb]; bbn[cb] = *(const bfx8*)(BBt + ((size_t)(gnx * 128 + cb * 32 + tl)) * GN + 8 * hh); }
;             if (PASS2) {
; #pragma unroll
;                 for (int ks = 0; ks < 4; ++ks) { cm[ks] = cmn[ks]; cmn[ks] = *(const bfx8*)(CMt + ((size_t)(gnx * GN + fr)) * 128 + 32 * ks + 8 * kq); }
;             }
;             float s0ar = 0.f, s0ai = 0.f, s0br = 0.f, s0bi = 0.f;
;             if (sample) { const size_t o0 = ((size_t)(2 * sb) * NG + g) * NP + lane, o1 = o0 + (size_t)NG * NP;
;                 s0ar = C.in(2)[o0]; s0ai = C.in(3)[o0]; s0br = C.in(2)[o1]; s0bi = C.in(3)[o1]; }
;             const bfx8 a = *(const LAS bfx8*)(XU + tl * XU_STRIDE + 16 * gi + 8 * hh);
; #pragma unroll
;             for (int cb = 0; cb < 4; ++cb) {
;                 v16f acc;
; #pragma unroll
;                 for (int r = 0; r < 16; ++r) acc[r] = 0.f;
;                 acc = __builtin_amdgcn_mfma_f32_32x32x16_bf16(bb[cb], a, acc, 0, 0, 0);
; #pragma unroll
;                 for (int rg = 0; rg < 4; ++rg) { v2u w; w.x = cvt_pk_c(acc[4 * rg], acc[4 * rg + 1]); w.y = cvt_pk_c(acc[4 * rg + 2], acc[4 * rg + 3]);
;                     *(LAS v2u*)(BH + tl * BH_STRIDE + cb * 32 + 8 * rg + 4 * hh) = w; }
;             }
;             LDS_FENCE();
;             {
;                 unsigned bu[32];
; #pragma unroll
;                 for (int t = 0; t < 32; ++t) bu[t] = *(const LAS unsigned*)(BH + t * BH_STRIDE + 2 * lane);
;                 LDS_FENCE();
;                 float xr = sr[gi], xi = si[gi];
; #pragma unroll
;                 for (int t = 0; t < 32; ++t) {
;                     if (sample && t == 0) { xr = s0ar; xi = s0ai; }
;                     if (sample && t == 16) { xr = s0br; xi = s0bi; }
;                     const float nr = fmaf(lr[gi], xr, fmaf(-li[gi], xi, bf_lo(bu[t]))), ni = fmaf(lr[gi], xi, fmaf(li[gi], xr, bf_hi(bu[t])));
;                     xr = nr; xi = ni;
;                     if (PASS2) {
.LBB0_666:
	s_waitcnt lgkmcnt(0)
	global_load_dwordx4 v[92:95], v[126:127], off
	global_load_dwordx4 v[88:91], v[128:129], off
	global_load_dwordx4 v[84:87], v[130:131], off
	global_load_dwordx4 v[80:83], v[132:133], off
	ds_read_b128 v[250:253], v192
	global_load_dwordx4 v[60:63], v[134:135], off
	global_load_dwordx4 v[56:59], v[134:135], off offset:1024
	global_load_dwordx4 v[48:51], v[134:135], off offset:2048
	global_load_dwordx4 v[52:55], v[134:135], off offset:3072
	s_waitcnt vmcnt(8) lgkmcnt(0)
	v_mfma_f32_32x32x16_bf16 v[0:15], v[250:253], v[76:79], 0
	v_mfma_f32_32x32x16_bf16 v[214:229], v[250:253], v[72:75], 0
	s_mov_b64 s[0:1], s[80:81]
	s_add_i32 s14, s14, 32
	s_add_i32 s15, s15, 1
	s_cmpk_eq_i32 s14, 0x80
	v_mfma_f32_32x32x16_bf16 v[234:249], v[250:253], v[68:71], 0
	v_mfma_f32_32x32x16_bf16 v[198:213], v[250:253], v[64:67], 0
	s_nop 11
	v_permlane32_swap_b32_e32 v0, v234
	v_permlane32_swap_b32_e32 v1, v235
	v_permlane32_swap_b32_e32 v2, v236
	v_permlane32_swap_b32_e32 v3, v237
	v_permlane32_swap_b32_e32 v4, v238
	v_permlane32_swap_b32_e32 v5, v239
	v_permlane32_swap_b32_e32 v6, v240
	v_permlane32_swap_b32_e32 v7, v241
	v_permlane32_swap_b32_e32 v8, v242
	v_permlane32_swap_b32_e32 v9, v243
	v_permlane32_swap_b32_e32 v10, v244
	v_permlane32_swap_b32_e32 v11, v245
	v_permlane32_swap_b32_e32 v12, v246
	v_permlane32_swap_b32_e32 v13, v247
	v_permlane32_swap_b32_e32 v14, v248
	v_permlane32_swap_b32_e32 v15, v249
	v_permlane32_swap_b32_e32 v214, v198
	v_permlane32_swap_b32_e32 v215, v199
	v_permlane32_swap_b32_e32 v216, v200
	v_permlane32_swap_b32_e32 v217, v201
	v_permlane32_swap_b32_e32 v218, v202
	v_permlane32_swap_b32_e32 v219, v203
	v_permlane32_swap_b32_e32 v220, v204
	v_permlane32_swap_b32_e32 v221, v205
	v_permlane32_swap_b32_e32 v222, v206
	v_permlane32_swap_b32_e32 v223, v207
	v_permlane32_swap_b32_e32 v224, v208
	v_permlane32_swap_b32_e32 v225, v209
	v_permlane32_swap_b32_e32 v226, v210
	v_permlane32_swap_b32_e32 v227, v211
	v_permlane32_swap_b32_e32 v228, v212
	v_permlane32_swap_b32_e32 v229, v213
	v_fma_f32 v0, -v174, v112, v0
	v_fma_f32 v214, v174, v114, v214
	v_fma_f32 v114, v173, v114, v0
	v_fma_f32 v112, v173, v112, v214
	v_cvt_pk_bf16_f32 v197, v114, v112
	ds_write_b32 v107, v197 offset:4608
	v_fma_f32 v1, -v174, v112, v1
	v_fma_f32 v215, v174, v114, v215
	v_fma_f32 v114, v173, v114, v1
	v_fma_f32 v112, v173, v112, v215
	v_cvt_pk_bf16_f32 v197, v114, v112
	ds_write_b32 v107, v197 offset:4880
	v_fma_f32 v2, -v174, v112, v2
	v_fma_f32 v216, v174, v114, v216
	v_fma_f32 v114, v173, v114, v2
	v_fma_f32 v112, v173, v112, v216
	v_cvt_pk_bf16_f32 v197, v114, v112
	ds_write_b32 v107, v197 offset:5152
	v_fma_f32 v3, -v174, v112, v3
	v_fma_f32 v217, v174, v114, v217
	v_fma_f32 v114, v173, v114, v3
	v_fma_f32 v112, v173, v112, v217
	v_cvt_pk_bf16_f32 v197, v114, v112
	ds_write_b32 v107, v197 offset:5424
	v_fma_f32 v234, -v174, v112, v234
	v_fma_f32 v198, v174, v114, v198
	v_fma_f32 v114, v173, v114, v234
	v_fma_f32 v112, v173, v112, v198
	v_cvt_pk_bf16_f32 v197, v114, v112
	ds_write_b32 v107, v197 offset:5696
	v_fma_f32 v235, -v174, v112, v235
	v_fma_f32 v199, v174, v114, v199
	v_fma_f32 v114, v173, v114, v235
	v_fma_f32 v112, v173, v112, v199
	v_cvt_pk_bf16_f32 v197, v114, v112
	ds_write_b32 v107, v197 offset:5968
	v_fma_f32 v236, -v174, v112, v236
	v_fma_f32 v200, v174, v114, v200
	v_fma_f32 v114, v173, v114, v236
	v_fma_f32 v112, v173, v112, v200
	v_cvt_pk_bf16_f32 v197, v114, v112
	ds_write_b32 v107, v197 offset:6240
	v_fma_f32 v237, -v174, v112, v237
	v_fma_f32 v201, v174, v114, v201
	v_fma_f32 v114, v173, v114, v237
	v_fma_f32 v112, v173, v112, v201
	v_cvt_pk_bf16_f32 v197, v114, v112
	ds_write_b32 v107, v197 offset:6512
	v_fma_f32 v4, -v174, v112, v4
	v_fma_f32 v218, v174, v114, v218
	v_fma_f32 v114, v173, v114, v4
	v_fma_f32 v112, v173, v112, v218
	v_cvt_pk_bf16_f32 v197, v114, v112
	ds_write_b32 v107, v197 offset:6784
	v_fma_f32 v5, -v174, v112, v5
	v_fma_f32 v219, v174, v114, v219
	v_fma_f32 v114, v173, v114, v5
	v_fma_f32 v112, v173, v112, v219
	v_cvt_pk_bf16_f32 v197, v114, v112
	ds_write_b32 v107, v197 offset:7056
	v_fma_f32 v6, -v174, v112, v6
	v_fma_f32 v220, v174, v114, v220
	v_fma_f32 v114, v173, v114, v6
	v_fma_f32 v112, v173, v112, v220
	v_cvt_pk_bf16_f32 v197, v114, v112
	ds_write_b32 v107, v197 offset:7328
	v_fma_f32 v7, -v174, v112, v7
	v_fma_f32 v221, v174, v114, v221
	v_fma_f32 v114, v173, v114, v7
	v_fma_f32 v112, v173, v112, v221
	v_cvt_pk_bf16_f32 v197, v114, v112
	ds_write_b32 v107, v197 offset:7600
	v_fma_f32 v238, -v174, v112, v238
	v_fma_f32 v202, v174, v114, v202
	v_fma_f32 v114, v173, v114, v238
	v_fma_f32 v112, v173, v112, v202
	v_cvt_pk_bf16_f32 v197, v114, v112
	ds_write_b32 v107, v197 offset:7872
	v_fma_f32 v239, -v174, v112, v239
	v_fma_f32 v203, v174, v114, v203
	v_fma_f32 v114, v173, v114, v239
	v_fma_f32 v112, v173, v112, v203
	v_cvt_pk_bf16_f32 v197, v114, v112
	ds_write_b32 v107, v197 offset:8144
	v_fma_f32 v240, -v174, v112, v240
	v_fma_f32 v204, v174, v114, v204
	v_fma_f32 v114, v173, v114, v240
	v_fma_f32 v112, v173, v112, v204
	v_cvt_pk_bf16_f32 v197, v114, v112
	ds_write_b32 v107, v197 offset:8416
	v_fma_f32 v241, -v174, v112, v241
	v_fma_f32 v205, v174, v114, v205
	v_fma_f32 v114, v173, v114, v241
	v_fma_f32 v112, v173, v112, v205
	v_cvt_pk_bf16_f32 v197, v114, v112
	ds_write_b32 v107, v197 offset:8688
	v_fma_f32 v8, -v174, v112, v8
	v_fma_f32 v222, v174, v114, v222
	v_fma_f32 v114, v173, v114, v8
	v_fma_f32 v112, v173, v112, v222
	v_cvt_pk_bf16_f32 v197, v114, v112
	ds_write_b32 v107, v197 offset:8960
	v_fma_f32 v9, -v174, v112, v9
	v_fma_f32 v223, v174, v114, v223
; __device__ __forceinline__ float bf_lo(unsigned w) { return __uint_as_float(w << 16); }
; __device__ __forceinline__ float bf_hi(unsigned w) { return __uint_as_float(w & 0xffff0000u); }
; #define LAS __attribute__((address_space(3)))
; #define LDS_FENCE() asm volatile("s_waitcnt lgkmcnt(0)" ::: "memory")
; __device__ __forceinline__ unsigned cvt_pk_nv(float lo, float hi) { unsigned r; asm("v_cvt_pk_bf16_f32 %0, %1, %2" : "=v"(r) : "v"(lo), "v"(hi)); return r; }
;     __device__ __forceinline__ float* out() const { return (float*)karg_in(33); }
; template <bool PASS2>
; __device__ __forceinline__ void s5_tile(const Ctx& C, int T, int sb_lo, int sb_hi, LAS unsigned char* lds, int wave, int lane) {
;     ...
;                 for (int t = 0; t < 32; ++t) {
;                     if (sample && t == 0) { xr = s0ar; xi = s0ai; }
;                     if (sample && t == 16) { xr = s0br; xi = s0bi; }
;                     const float nr = fmaf(lr[gi], xr, fmaf(-li[gi], xi, bf_lo(bu[t]))), ni = fmaf(lr[gi], xi, fmaf(li[gi], xr, bf_hi(bu[t])));
;                     xr = nr; xi = ni;
;                     if (PASS2) {
;                         *(LAS unsigned*)(BH + t * BH_STRIDE + 2 * lane) = cvt_pk_nv(xr, xi);
;                         if (sample && (t & 15) == 15) { const int seq = 2 * sb + (t >> 4);
;                             C.out()[OFF_SRE_S + ((size_t)seq * NG + g) * NP + lane] = xr; C.out()[OFF_SIM_S + ((size_t)seq * NG + g) * NP + lane] = xi; }
;                     }
;                 }
;                 sr[gi] = xr; si[gi] = xi;
;             }
;             LDS_FENCE();
;             if (PASS2) {
; #pragma unroll
;                 for (int rb = 0; rb < 2; ++rb) {
;                     v4f acc = (v4f){0.f, 0.f, 0.f, 0.f};
; #pragma unroll
;                     for (int ks = 0; ks < 4; ++ks) {
;                         const bfx8 sa = *(const LAS bfx8*)(BH + (16 * rb + fr) * BH_STRIDE + 32 * ks + 8 * kq);
;                         acc = __builtin_amdgcn_mfma_f32_16x16x32_bf16(sa, cm[ks], acc, 0, 0, 0);
;                     }
; #pragma unroll
;                     for (int r = 0; r < 4; ++r) {
;                         LAS bf16* up = XU + (16 * rb + 4 * kq + r) * XU_STRIDE + 16 * gi + fr;
;                         const float u = __uint_as_float((unsigned)(*up) << 16);
	v_fma_f32 v114, v173, v114, v9
	v_fma_f32 v112, v173, v112, v223
	v_cvt_pk_bf16_f32 v197, v114, v112
	ds_write_b32 v107, v197 offset:9232
	v_fma_f32 v10, -v174, v112, v10
	v_fma_f32 v224, v174, v114, v224
	v_fma_f32 v114, v173, v114, v10
	v_fma_f32 v112, v173, v112, v224
	v_cvt_pk_bf16_f32 v197, v114, v112
	ds_write_b32 v107, v197 offset:9504
	v_fma_f32 v11, -v174, v112, v11
	v_fma_f32 v225, v174, v114, v225
	v_fma_f32 v114, v173, v114, v11
	v_fma_f32 v112, v173, v112, v225
	v_cvt_pk_bf16_f32 v197, v114, v112
	ds_write_b32 v107, v197 offset:9776
	v_fma_f32 v242, -v174, v112, v242
	v_fma_f32 v206, v174, v114, v206
	v_fma_f32 v114, v173, v114, v242
	v_fma_f32 v112, v173, v112, v206
	v_cvt_pk_bf16_f32 v197, v114, v112
	ds_write_b32 v107, v197 offset:10048
	v_fma_f32 v243, -v174, v112, v243
	v_fma_f32 v207, v174, v114, v207
	v_fma_f32 v114, v173, v114, v243
	v_fma_f32 v112, v173, v112, v207
	v_cvt_pk_bf16_f32 v197, v114, v112
	ds_write_b32 v107, v197 offset:10320
	v_fma_f32 v244, -v174, v112, v244
	v_fma_f32 v208, v174, v114, v208
	v_fma_f32 v114, v173, v114, v244
	v_fma_f32 v112, v173, v112, v208
	v_cvt_pk_bf16_f32 v197, v114, v112
	ds_write_b32 v107, v197 offset:10592
	v_fma_f32 v245, -v174, v112, v245
	v_fma_f32 v209, v174, v114, v209
	v_fma_f32 v114, v173, v114, v245
	v_fma_f32 v112, v173, v112, v209
	v_cvt_pk_bf16_f32 v197, v114, v112
	ds_write_b32 v107, v197 offset:10864
	v_fma_f32 v12, -v174, v112, v12
	v_fma_f32 v226, v174, v114, v226
	v_fma_f32 v114, v173, v114, v12
	v_fma_f32 v112, v173, v112, v226
	v_cvt_pk_bf16_f32 v197, v114, v112
	ds_write_b32 v107, v197 offset:11136
	v_fma_f32 v13, -v174, v112, v13
	v_fma_f32 v227, v174, v114, v227
	v_fma_f32 v114, v173, v114, v13
	v_fma_f32 v112, v173, v112, v227
	v_cvt_pk_bf16_f32 v197, v114, v112
	ds_write_b32 v107, v197 offset:11408
	v_fma_f32 v14, -v174, v112, v14
	v_fma_f32 v228, v174, v114, v228
	v_fma_f32 v114, v173, v114, v14
	v_fma_f32 v112, v173, v112, v228
	v_cvt_pk_bf16_f32 v197, v114, v112
	ds_write_b32 v107, v197 offset:11680
	v_fma_f32 v15, -v174, v112, v15
	v_fma_f32 v229, v174, v114, v229
	v_fma_f32 v114, v173, v114, v15
	v_fma_f32 v112, v173, v112, v229
	v_cvt_pk_bf16_f32 v197, v114, v112
	ds_write_b32 v107, v197 offset:11952
	v_fma_f32 v246, -v174, v112, v246
	v_fma_f32 v210, v174, v114, v210
	v_fma_f32 v114, v173, v114, v246
	v_fma_f32 v112, v173, v112, v210
	v_cvt_pk_bf16_f32 v197, v114, v112
	ds_write_b32 v107, v197 offset:12224
	v_fma_f32 v247, -v174, v112, v247
	v_fma_f32 v211, v174, v114, v211
	v_fma_f32 v114, v173, v114, v247
	v_fma_f32 v112, v173, v112, v211
	v_cvt_pk_bf16_f32 v197, v114, v112
	ds_write_b32 v107, v197 offset:12496
	v_fma_f32 v248, -v174, v112, v248
	v_fma_f32 v212, v174, v114, v212
	v_fma_f32 v114, v173, v114, v248
	v_fma_f32 v112, v173, v112, v212
	v_cvt_pk_bf16_f32 v197, v114, v112
	ds_write_b32 v107, v197 offset:12768
	v_fma_f32 v249, -v174, v112, v249
	v_fma_f32 v213, v174, v114, v213
	v_fma_f32 v114, v173, v114, v249
	v_fma_f32 v112, v173, v112, v213
	v_cvt_pk_bf16_f32 v197, v114, v112
	ds_write_b32 v107, v197 offset:13040
	s_waitcnt lgkmcnt(0)
	ds_read_b128 v[214:217], v194 offset:4608
	ds_read_b128 v[218:221], v194 offset:4672
	ds_read_b128 v[222:225], v194 offset:4736
	ds_read_b128 v[226:229], v194 offset:4800
	ds_read_b128 v[234:237], v194 offset:8960
	ds_read_b128 v[238:241], v194 offset:9024
	ds_read_b128 v[242:245], v194 offset:9088
	ds_read_b128 v[246:249], v194 offset:9152
	ds_read_u16 v8, v195
	ds_read_u16 v9, v195 offset:144
	ds_read_u16 v10, v195 offset:288
	ds_read_u16 v11, v195 offset:432
	ds_read_u16 v12, v195 offset:2304
	ds_read_u16 v13, v195 offset:2448
	ds_read_u16 v14, v195 offset:2592
	ds_read_u16 v15, v195 offset:2736
	s_waitcnt lgkmcnt(8)
	v_mfma_f32_16x16x32_bf16 v[0:3], v[214:217], v[44:47], 0
	v_mfma_f32_16x16x32_bf16 v[4:7], v[234:237], v[44:47], 0
	v_mfma_f32_16x16x32_bf16 v[0:3], v[218:221], v[40:43], v[0:3]
	v_mfma_f32_16x16x32_bf16 v[4:7], v[238:241], v[40:43], v[4:7]
	v_mfma_f32_16x16x32_bf16 v[0:3], v[222:225], v[36:39], v[0:3]
	v_mfma_f32_16x16x32_bf16 v[4:7], v[242:245], v[36:39], v[4:7]
	v_mfma_f32_16x16x32_bf16 v[0:3], v[226:229], v[32:35], v[0:3]
	v_mfma_f32_16x16x32_bf16 v[4:7], v[246:249], v[32:35], v[4:7]
	s_waitcnt lgkmcnt(0)
; __device__ __forceinline__ float gelu_t(float x) { const float u = 1.5957691216057308f * (x + 0.044715f * x * x * x); return x * sigmoid_f(u); }
; #define LAS __attribute__((address_space(3)))
; template <bool PASS2>
; __device__ __forceinline__ void s5_tile(const Ctx& C, int T, int sb_lo, int sb_hi, LAS unsigned char* lds, int wave, int lane) {
;     ...
;         for (int gi = 0; gi < 4; ++gi) {
;             const int g = wave * 4 + gi, gnx = wave * 4 + ((gi + 1) & 3);
;             bfx8 bb[4], cm[4];
; #pragma unroll
;             for (int cb = 0; cb < 4; ++cb) { bb[cb] = bbn[cb]; bbn[cb] = *(const bfx8*)(BBt + ((size_t)(gnx * 128 + cb * 32 + tl)) * GN + 8 * hh); }
;             if (PASS2) {
; #pragma unroll
;                 for (int ks = 0; ks < 4; ++ks) { cm[ks] = cmn[ks]; cmn[ks] = *(const bfx8*)(CMt + ((size_t)(gnx * GN + fr)) * 128 + 32 * ks + 8 * kq); }
;             }
;             float s0ar = 0.f, s0ai = 0.f, s0br = 0.f, s0bi = 0.f;
;             if (sample) { const size_t o0 = ((size_t)(2 * sb) * NG + g) * NP + lane, o1 = o0 + (size_t)NG * NP;
;                 s0ar = C.in(2)[o0]; s0ai = C.in(3)[o0]; s0br = C.in(2)[o1]; s0bi = C.in(3)[o1]; }
;             const bfx8 a = *(const LAS bfx8*)(XU + tl * XU_STRIDE + 16 * gi + 8 * hh);
; #pragma unroll
;             for (int cb = 0; cb < 4; ++cb) {
;                 v16f acc;
; #pragma unroll
;                 for (int r = 0; r < 16; ++r) acc[r] = 0.f;
;                 acc = __builtin_amdgcn_mfma_f32_32x32x16_bf16(bb[cb], a, acc, 0, 0, 0);
;     ...
;             if (PASS2) {
; #pragma unroll
;                 for (int rb = 0; rb < 2; ++rb) {
;                     v4f acc = (v4f){0.f, 0.f, 0.f, 0.f};
; #pragma unroll
;                     for (int ks = 0; ks < 4; ++ks) {
;                         const bfx8 sa = *(const LAS bfx8*)(BH + (16 * rb + fr) * BH_STRIDE + 32 * ks + 8 * kq);
;                         acc = __builtin_amdgcn_mfma_f32_16x16x32_bf16(sa, cm[ks], acc, 0, 0, 0);
;                     }
; #pragma unroll
;                     for (int r = 0; r < 4; ++r) {
;                         LAS bf16* up = XU + (16 * rb + 4 * kq + r) * XU_STRIDE + 16 * gi + fr;
;                         const float u = __uint_as_float((unsigned)(*up) << 16);
;                         *up = f2bf(gelu_t(acc[r] + dsk[gi] * u));
;                     }
	v_lshlrev_b32_e32 v8, 16, v8
	v_lshlrev_b32_e32 v9, 16, v9
	v_lshlrev_b32_e32 v10, 16, v10
	v_lshlrev_b32_e32 v11, 16, v11
	v_lshlrev_b32_e32 v12, 16, v12
	v_lshlrev_b32_e32 v13, 16, v13
	v_lshlrev_b32_e32 v14, 16, v14
	v_lshlrev_b32_e32 v15, 16, v15
	v_fma_f32 v0, v175, v8, v0
	v_fma_f32 v1, v175, v9, v1
	v_fma_f32 v2, v175, v10, v2
	v_fma_f32 v3, v175, v11, v3
	v_fma_f32 v4, v175, v12, v4
	v_fma_f32 v5, v175, v13, v5
	v_fma_f32 v6, v175, v14, v6
	v_fma_f32 v7, v175, v15, v7
	v_mul_f32_e32 v198, 0x3d372713, v0
	v_mul_f32_e32 v199, 0x3d372713, v1
	v_mul_f32_e32 v200, 0x3d372713, v2
	v_mul_f32_e32 v201, 0x3d372713, v3
	v_mul_f32_e32 v202, 0x3d372713, v4
	v_mul_f32_e32 v203, 0x3d372713, v5
	v_mul_f32_e32 v204, 0x3d372713, v6
	v_mul_f32_e32 v205, 0x3d372713, v7
	v_mul_f32_e32 v198, v0, v198
	v_mul_f32_e32 v199, v1, v199
	v_mul_f32_e32 v200, v2, v200
	v_mul_f32_e32 v201, v3, v201
	v_mul_f32_e32 v202, v4, v202
	v_mul_f32_e32 v203, v5, v203
	v_mul_f32_e32 v204, v6, v204
	v_mul_f32_e32 v205, v7, v205
	v_fma_f32 v198, v0, v198, v0
	v_fma_f32 v199, v1, v199, v1
	v_fma_f32 v200, v2, v200, v2
	v_fma_f32 v201, v3, v201, v3
	v_fma_f32 v202, v4, v202, v4
	v_fma_f32 v203, v5, v203, v5
	v_fma_f32 v204, v6, v204, v6
	v_fma_f32 v205, v7, v205, v7
	v_mul_f32_e32 v198, 0x3fcc422a, v198
	v_mul_f32_e32 v199, 0x3fcc422a, v199
	v_mul_f32_e32 v200, 0x3fcc422a, v200
	v_mul_f32_e32 v201, 0x3fcc422a, v201
	v_mul_f32_e32 v202, 0x3fcc422a, v202
	v_mul_f32_e32 v203, 0x3fcc422a, v203
	v_mul_f32_e32 v204, 0x3fcc422a, v204
	v_mul_f32_e32 v205, 0x3fcc422a, v205
	v_mul_f32_e32 v198, 0xbfb8aa3b, v198
	v_mul_f32_e32 v199, 0xbfb8aa3b, v199
	v_mul_f32_e32 v200, 0xbfb8aa3b, v200
	v_mul_f32_e32 v201, 0xbfb8aa3b, v201
	v_mul_f32_e32 v202, 0xbfb8aa3b, v202
	v_mul_f32_e32 v203, 0xbfb8aa3b, v203
	v_mul_f32_e32 v204, 0xbfb8aa3b, v204
	v_mul_f32_e32 v205, 0xbfb8aa3b, v205
	v_exp_f32_e32 v198, v198
	v_exp_f32_e32 v199, v199
	v_exp_f32_e32 v200, v200
	v_exp_f32_e32 v201, v201
	v_exp_f32_e32 v202, v202
	v_exp_f32_e32 v203, v203
	v_exp_f32_e32 v204, v204
	v_exp_f32_e32 v205, v205
	v_add_f32_e32 v198, 1.0, v198
	v_add_f32_e32 v199, 1.0, v199
	v_add_f32_e32 v200, 1.0, v200
	v_add_f32_e32 v201, 1.0, v201
	v_add_f32_e32 v202, 1.0, v202
	v_add_f32_e32 v203, 1.0, v203
	v_add_f32_e32 v204, 1.0, v204
	v_add_f32_e32 v205, 1.0, v205
	v_rcp_f32_e32 v198, v198
	v_rcp_f32_e32 v199, v199
	v_rcp_f32_e32 v200, v200
	v_rcp_f32_e32 v201, v201
	v_rcp_f32_e32 v202, v202
	v_rcp_f32_e32 v203, v203
	v_rcp_f32_e32 v204, v204
	v_rcp_f32_e32 v205, v205
	v_mul_f32_e32 v0, v0, v198
	v_mul_f32_e32 v1, v1, v199
	v_mul_f32_e32 v2, v2, v200
	v_mul_f32_e32 v3, v3, v201
	v_mul_f32_e32 v4, v4, v202
	v_mul_f32_e32 v5, v5, v203
	v_mul_f32_e32 v6, v6, v204
	v_mul_f32_e32 v7, v7, v205
	v_cvt_pk_bf16_f32 v0, v0, v101
	v_cvt_pk_bf16_f32 v1, v1, v101
	v_cvt_pk_bf16_f32 v2, v2, v101
	v_cvt_pk_bf16_f32 v3, v3, v101
	v_cvt_pk_bf16_f32 v4, v4, v101
	v_cvt_pk_bf16_f32 v5, v5, v101
	v_cvt_pk_bf16_f32 v6, v6, v101
	v_cvt_pk_bf16_f32 v7, v7, v101
	ds_write_b16 v195, v0
	ds_write_b16 v195, v1 offset:144
	ds_write_b16 v195, v2 offset:288
	ds_write_b16 v195, v3 offset:432
	ds_write_b16 v195, v4 offset:2304
	ds_write_b16 v195, v5 offset:2448
	ds_write_b16 v195, v6 offset:2592
	ds_write_b16 v195, v7 offset:2736
	s_waitcnt lgkmcnt(0)
	global_load_dwordx4 v[76:79], v[136:137], off
	global_load_dwordx4 v[72:75], v[138:139], off
	global_load_dwordx4 v[68:71], v[140:141], off
	global_load_dwordx4 v[64:67], v[142:143], off
	ds_read_b128 v[250:253], v192 offset:32
	s_waitcnt vmcnt(11) lgkmcnt(0)
	v_mfma_f32_32x32x16_bf16 v[0:15], v[250:253], v[92:95], 0
	global_load_dwordx4 v[44:47], v[144:145], off
	global_load_dwordx4 v[40:43], v[144:145], off offset:1024
	global_load_dwordx4 v[32:35], v[144:145], off offset:2048
	global_load_dwordx4 v[36:39], v[144:145], off offset:3072
	s_waitcnt vmcnt(14)
	v_mfma_f32_32x32x16_bf16 v[214:229], v[250:253], v[88:91], 0
	s_waitcnt vmcnt(13)
	v_mfma_f32_32x32x16_bf16 v[234:249], v[250:253], v[84:87], 0
	s_waitcnt vmcnt(12)
	v_mfma_f32_32x32x16_bf16 v[198:213], v[250:253], v[80:83], 0
	s_nop 11
	v_permlane32_swap_b32_e32 v0, v234
	v_permlane32_swap_b32_e32 v1, v235
	v_permlane32_swap_b32_e32 v2, v236
	v_permlane32_swap_b32_e32 v3, v237
	v_permlane32_swap_b32_e32 v4, v238
	v_permlane32_swap_b32_e32 v5, v239
	v_permlane32_swap_b32_e32 v6, v240
	v_permlane32_swap_b32_e32 v7, v241
	v_permlane32_swap_b32_e32 v8, v242
	v_permlane32_swap_b32_e32 v9, v243
	v_permlane32_swap_b32_e32 v10, v244
	v_permlane32_swap_b32_e32 v11, v245
	v_permlane32_swap_b32_e32 v12, v246
	v_permlane32_swap_b32_e32 v13, v247
	v_permlane32_swap_b32_e32 v14, v248
	v_permlane32_swap_b32_e32 v15, v249
	v_permlane32_swap_b32_e32 v214, v198
	v_permlane32_swap_b32_e32 v215, v199
	v_permlane32_swap_b32_e32 v216, v200
	v_permlane32_swap_b32_e32 v217, v201
	v_permlane32_swap_b32_e32 v218, v202
	v_permlane32_swap_b32_e32 v219, v203
	v_permlane32_swap_b32_e32 v220, v204
	v_permlane32_swap_b32_e32 v221, v205
	v_permlane32_swap_b32_e32 v222, v206
	v_permlane32_swap_b32_e32 v223, v207
	v_permlane32_swap_b32_e32 v224, v208
	v_permlane32_swap_b32_e32 v225, v209
	v_permlane32_swap_b32_e32 v226, v210
	v_permlane32_swap_b32_e32 v227, v211
	v_permlane32_swap_b32_e32 v228, v212
	v_permlane32_swap_b32_e32 v229, v213
	v_fma_f32 v0, -v177, v113, v0
	v_fma_f32 v214, v177, v115, v214
	v_fma_f32 v115, v176, v115, v0
	v_fma_f32 v113, v176, v113, v214
	v_cvt_pk_bf16_f32 v197, v115, v113
	ds_write_b32 v107, v197 offset:4608
	v_fma_f32 v1, -v177, v113, v1
	v_fma_f32 v215, v177, v115, v215
	v_fma_f32 v115, v176, v115, v1
	v_fma_f32 v113, v176, v113, v215
	v_cvt_pk_bf16_f32 v197, v115, v113
; __device__ __forceinline__ float bf_lo(unsigned w) { return __uint_as_float(w << 16); }
; __device__ __forceinline__ float bf_hi(unsigned w) { return __uint_as_float(w & 0xffff0000u); }
; #define LAS __attribute__((address_space(3)))
; __device__ __forceinline__ unsigned cvt_pk_nv(float lo, float hi) { unsigned r; asm("v_cvt_pk_bf16_f32 %0, %1, %2" : "=v"(r) : "v"(lo), "v"(hi)); return r; }
; template <bool PASS2>
; __device__ __forceinline__ void s5_tile(const Ctx& C, int T, int sb_lo, int sb_hi, LAS unsigned char* lds, int wave, int lane) {
;     ...
;                 for (int t = 0; t < 32; ++t) {
;                     if (sample && t == 0) { xr = s0ar; xi = s0ai; }
;                     if (sample && t == 16) { xr = s0br; xi = s0bi; }
;                     const float nr = fmaf(lr[gi], xr, fmaf(-li[gi], xi, bf_lo(bu[t]))), ni = fmaf(lr[gi], xi, fmaf(li[gi], xr, bf_hi(bu[t])));
;                     xr = nr; xi = ni;
;                     if (PASS2) {
;                         *(LAS unsigned*)(BH + t * BH_STRIDE + 2 * lane) = cvt_pk_nv(xr, xi);
	ds_write_b32 v107, v197 offset:4880
	v_fma_f32 v2, -v177, v113, v2
	v_fma_f32 v216, v177, v115, v216
	v_fma_f32 v115, v176, v115, v2
	v_fma_f32 v113, v176, v113, v216
	v_cvt_pk_bf16_f32 v197, v115, v113
	ds_write_b32 v107, v197 offset:5152
	v_fma_f32 v3, -v177, v113, v3
	v_fma_f32 v217, v177, v115, v217
	v_fma_f32 v115, v176, v115, v3
	v_fma_f32 v113, v176, v113, v217
	v_cvt_pk_bf16_f32 v197, v115, v113
	ds_write_b32 v107, v197 offset:5424
	v_fma_f32 v234, -v177, v113, v234
	v_fma_f32 v198, v177, v115, v198
	v_fma_f32 v115, v176, v115, v234
	v_fma_f32 v113, v176, v113, v198
	v_cvt_pk_bf16_f32 v197, v115, v113
	ds_write_b32 v107, v197 offset:5696
	v_fma_f32 v235, -v177, v113, v235
	v_fma_f32 v199, v177, v115, v199
	v_fma_f32 v115, v176, v115, v235
	v_fma_f32 v113, v176, v113, v199
	v_cvt_pk_bf16_f32 v197, v115, v113
	ds_write_b32 v107, v197 offset:5968
	v_fma_f32 v236, -v177, v113, v236
	v_fma_f32 v200, v177, v115, v200
	v_fma_f32 v115, v176, v115, v236
	v_fma_f32 v113, v176, v113, v200
	v_cvt_pk_bf16_f32 v197, v115, v113
	ds_write_b32 v107, v197 offset:6240
	v_fma_f32 v237, -v177, v113, v237
	v_fma_f32 v201, v177, v115, v201
	v_fma_f32 v115, v176, v115, v237
	v_fma_f32 v113, v176, v113, v201
	v_cvt_pk_bf16_f32 v197, v115, v113
	ds_write_b32 v107, v197 offset:6512
	v_fma_f32 v4, -v177, v113, v4
	v_fma_f32 v218, v177, v115, v218
	v_fma_f32 v115, v176, v115, v4
	v_fma_f32 v113, v176, v113, v218
	v_cvt_pk_bf16_f32 v197, v115, v113
	ds_write_b32 v107, v197 offset:6784
	v_fma_f32 v5, -v177, v113, v5
	v_fma_f32 v219, v177, v115, v219
	v_fma_f32 v115, v176, v115, v5
	v_fma_f32 v113, v176, v113, v219
	v_cvt_pk_bf16_f32 v197, v115, v113
	ds_write_b32 v107, v197 offset:7056
	v_fma_f32 v6, -v177, v113, v6
	v_fma_f32 v220, v177, v115, v220
	v_fma_f32 v115, v176, v115, v6
	v_fma_f32 v113, v176, v113, v220
	v_cvt_pk_bf16_f32 v197, v115, v113
	ds_write_b32 v107, v197 offset:7328
	v_fma_f32 v7, -v177, v113, v7
	v_fma_f32 v221, v177, v115, v221
	v_fma_f32 v115, v176, v115, v7
	v_fma_f32 v113, v176, v113, v221
	v_cvt_pk_bf16_f32 v197, v115, v113
	ds_write_b32 v107, v197 offset:7600
	v_fma_f32 v238, -v177, v113, v238
	v_fma_f32 v202, v177, v115, v202
	v_fma_f32 v115, v176, v115, v238
	v_fma_f32 v113, v176, v113, v202
	v_cvt_pk_bf16_f32 v197, v115, v113
	ds_write_b32 v107, v197 offset:7872
	v_fma_f32 v239, -v177, v113, v239
	v_fma_f32 v203, v177, v115, v203
	v_fma_f32 v115, v176, v115, v239
	v_fma_f32 v113, v176, v113, v203
	v_cvt_pk_bf16_f32 v197, v115, v113
	ds_write_b32 v107, v197 offset:8144
	v_fma_f32 v240, -v177, v113, v240
	v_fma_f32 v204, v177, v115, v204
	v_fma_f32 v115, v176, v115, v240
	v_fma_f32 v113, v176, v113, v204
	v_cvt_pk_bf16_f32 v197, v115, v113
	ds_write_b32 v107, v197 offset:8416
	v_fma_f32 v241, -v177, v113, v241
	v_fma_f32 v205, v177, v115, v205
	v_fma_f32 v115, v176, v115, v241
	v_fma_f32 v113, v176, v113, v205
	v_cvt_pk_bf16_f32 v197, v115, v113
	ds_write_b32 v107, v197 offset:8688
	v_fma_f32 v8, -v177, v113, v8
	v_fma_f32 v222, v177, v115, v222
	v_fma_f32 v115, v176, v115, v8
	v_fma_f32 v113, v176, v113, v222
	v_cvt_pk_bf16_f32 v197, v115, v113
	ds_write_b32 v107, v197 offset:8960
	v_fma_f32 v9, -v177, v113, v9
	v_fma_f32 v223, v177, v115, v223
	v_fma_f32 v115, v176, v115, v9
	v_fma_f32 v113, v176, v113, v223
	v_cvt_pk_bf16_f32 v197, v115, v113
	ds_write_b32 v107, v197 offset:9232
	v_fma_f32 v10, -v177, v113, v10
	v_fma_f32 v224, v177, v115, v224
	v_fma_f32 v115, v176, v115, v10
	v_fma_f32 v113, v176, v113, v224
	v_cvt_pk_bf16_f32 v197, v115, v113
	ds_write_b32 v107, v197 offset:9504
	v_fma_f32 v11, -v177, v113, v11
	v_fma_f32 v225, v177, v115, v225
	v_fma_f32 v115, v176, v115, v11
	v_fma_f32 v113, v176, v113, v225
	v_cvt_pk_bf16_f32 v197, v115, v113
	ds_write_b32 v107, v197 offset:9776
	v_fma_f32 v242, -v177, v113, v242
	v_fma_f32 v206, v177, v115, v206
	v_fma_f32 v115, v176, v115, v242
	v_fma_f32 v113, v176, v113, v206
	v_cvt_pk_bf16_f32 v197, v115, v113
	ds_write_b32 v107, v197 offset:10048
	v_fma_f32 v243, -v177, v113, v243
	v_fma_f32 v207, v177, v115, v207
	v_fma_f32 v115, v176, v115, v243
	v_fma_f32 v113, v176, v113, v207
	v_cvt_pk_bf16_f32 v197, v115, v113
	ds_write_b32 v107, v197 offset:10320
	v_fma_f32 v244, -v177, v113, v244
	v_fma_f32 v208, v177, v115, v208
	v_fma_f32 v115, v176, v115, v244
	v_fma_f32 v113, v176, v113, v208
	v_cvt_pk_bf16_f32 v197, v115, v113
	ds_write_b32 v107, v197 offset:10592
	v_fma_f32 v245, -v177, v113, v245
	v_fma_f32 v209, v177, v115, v209
	v_fma_f32 v115, v176, v115, v245
	v_fma_f32 v113, v176, v113, v209
	v_cvt_pk_bf16_f32 v197, v115, v113
	ds_write_b32 v107, v197 offset:10864
	v_fma_f32 v12, -v177, v113, v12
	v_fma_f32 v226, v177, v115, v226
	v_fma_f32 v115, v176, v115, v12
	v_fma_f32 v113, v176, v113, v226
	v_cvt_pk_bf16_f32 v197, v115, v113
	ds_write_b32 v107, v197 offset:11136
	v_fma_f32 v13, -v177, v113, v13
	v_fma_f32 v227, v177, v115, v227
	v_fma_f32 v115, v176, v115, v13
	v_fma_f32 v113, v176, v113, v227
	v_cvt_pk_bf16_f32 v197, v115, v113
	ds_write_b32 v107, v197 offset:11408
	v_fma_f32 v14, -v177, v113, v14
	v_fma_f32 v228, v177, v115, v228
	v_fma_f32 v115, v176, v115, v14
	v_fma_f32 v113, v176, v113, v228
	v_cvt_pk_bf16_f32 v197, v115, v113
	ds_write_b32 v107, v197 offset:11680
	v_fma_f32 v15, -v177, v113, v15
	v_fma_f32 v229, v177, v115, v229
	v_fma_f32 v115, v176, v115, v15
	v_fma_f32 v113, v176, v113, v229
	v_cvt_pk_bf16_f32 v197, v115, v113
	ds_write_b32 v107, v197 offset:11952
	v_fma_f32 v246, -v177, v113, v246
	v_fma_f32 v210, v177, v115, v210
	v_fma_f32 v115, v176, v115, v246
	v_fma_f32 v113, v176, v113, v210
	v_cvt_pk_bf16_f32 v197, v115, v113
	ds_write_b32 v107, v197 offset:12224
	v_fma_f32 v247, -v177, v113, v247
	v_fma_f32 v211, v177, v115, v211
	v_fma_f32 v115, v176, v115, v247
	v_fma_f32 v113, v176, v113, v211
	v_cvt_pk_bf16_f32 v197, v115, v113
	ds_write_b32 v107, v197 offset:12496
	v_fma_f32 v248, -v177, v113, v248
	v_fma_f32 v212, v177, v115, v212
	v_fma_f32 v115, v176, v115, v248
	v_fma_f32 v113, v176, v113, v212
	v_cvt_pk_bf16_f32 v197, v115, v113
	ds_write_b32 v107, v197 offset:12768
	v_fma_f32 v249, -v177, v113, v249
	v_fma_f32 v213, v177, v115, v213
	v_fma_f32 v115, v176, v115, v249
	v_fma_f32 v113, v176, v113, v213
	v_cvt_pk_bf16_f32 v197, v115, v113
	ds_write_b32 v107, v197 offset:13040
	s_waitcnt lgkmcnt(0)
; __device__ __forceinline__ float gelu_t(float x) { const float u = 1.5957691216057308f * (x + 0.044715f * x * x * x); return x * sigmoid_f(u); }
; #define LAS __attribute__((address_space(3)))
; template <bool PASS2>
; __device__ __forceinline__ void s5_tile(const Ctx& C, int T, int sb_lo, int sb_hi, LAS unsigned char* lds, int wave, int lane) {
;     ...
;         for (int gi = 0; gi < 4; ++gi) {
;             const int g = wave * 4 + gi, gnx = wave * 4 + ((gi + 1) & 3);
;             bfx8 bb[4], cm[4];
; #pragma unroll
;             for (int cb = 0; cb < 4; ++cb) { bb[cb] = bbn[cb]; bbn[cb] = *(const bfx8*)(BBt + ((size_t)(gnx * 128 + cb * 32 + tl)) * GN + 8 * hh); }
;             if (PASS2) {
; #pragma unroll
;                 for (int ks = 0; ks < 4; ++ks) { cm[ks] = cmn[ks]; cmn[ks] = *(const bfx8*)(CMt + ((size_t)(gnx * GN + fr)) * 128 + 32 * ks + 8 * kq); }
;             }
;             float s0ar = 0.f, s0ai = 0.f, s0br = 0.f, s0bi = 0.f;
;             if (sample) { const size_t o0 = ((size_t)(2 * sb) * NG + g) * NP + lane, o1 = o0 + (size_t)NG * NP;
;                 s0ar = C.in(2)[o0]; s0ai = C.in(3)[o0]; s0br = C.in(2)[o1]; s0bi = C.in(3)[o1]; }
;             const bfx8 a = *(const LAS bfx8*)(XU + tl * XU_STRIDE + 16 * gi + 8 * hh);
; #pragma unroll
;             for (int cb = 0; cb < 4; ++cb) {
;                 v16f acc;
; #pragma unroll
;                 for (int r = 0; r < 16; ++r) acc[r] = 0.f;
;                 acc = __builtin_amdgcn_mfma_f32_32x32x16_bf16(bb[cb], a, acc, 0, 0, 0);
;     ...
;             if (PASS2) {
; #pragma unroll
;                 for (int rb = 0; rb < 2; ++rb) {
;                     v4f acc = (v4f){0.f, 0.f, 0.f, 0.f};
; #pragma unroll
;                     for (int ks = 0; ks < 4; ++ks) {
;                         const bfx8 sa = *(const LAS bfx8*)(BH + (16 * rb + fr) * BH_STRIDE + 32 * ks + 8 * kq);
;                         acc = __builtin_amdgcn_mfma_f32_16x16x32_bf16(sa, cm[ks], acc, 0, 0, 0);
;                     }
; #pragma unroll
;                     for (int r = 0; r < 4; ++r) {
;                         LAS bf16* up = XU + (16 * rb + 4 * kq + r) * XU_STRIDE + 16 * gi + fr;
;                         const float u = __uint_as_float((unsigned)(*up) << 16);
;                         *up = f2bf(gelu_t(acc[r] + dsk[gi] * u));
;                     }
	ds_read_b128 v[214:217], v194 offset:4608
	ds_read_b128 v[218:221], v194 offset:4672
	ds_read_b128 v[222:225], v194 offset:4736
	ds_read_b128 v[226:229], v194 offset:4800
	ds_read_b128 v[234:237], v194 offset:8960
	ds_read_b128 v[238:241], v194 offset:9024
	ds_read_b128 v[242:245], v194 offset:9088
	ds_read_b128 v[246:249], v194 offset:9152
	ds_read_u16 v8, v195 offset:32
	ds_read_u16 v9, v195 offset:176
	ds_read_u16 v10, v195 offset:320
	ds_read_u16 v11, v195 offset:464
	ds_read_u16 v12, v195 offset:2336
	ds_read_u16 v13, v195 offset:2480
	ds_read_u16 v14, v195 offset:2624
	ds_read_u16 v15, v195 offset:2768
	s_waitcnt vmcnt(8) lgkmcnt(8)
	v_mfma_f32_16x16x32_bf16 v[0:3], v[214:217], v[60:63], 0
	v_mfma_f32_16x16x32_bf16 v[4:7], v[234:237], v[60:63], 0
	v_mfma_f32_16x16x32_bf16 v[0:3], v[218:221], v[56:59], v[0:3]
	v_mfma_f32_16x16x32_bf16 v[4:7], v[238:241], v[56:59], v[4:7]
	v_mfma_f32_16x16x32_bf16 v[0:3], v[222:225], v[48:51], v[0:3]
	v_mfma_f32_16x16x32_bf16 v[4:7], v[242:245], v[48:51], v[4:7]
	v_mfma_f32_16x16x32_bf16 v[0:3], v[226:229], v[52:55], v[0:3]
	v_mfma_f32_16x16x32_bf16 v[4:7], v[246:249], v[52:55], v[4:7]
	s_waitcnt lgkmcnt(0)
	v_lshlrev_b32_e32 v8, 16, v8
	v_lshlrev_b32_e32 v9, 16, v9
	v_lshlrev_b32_e32 v10, 16, v10
	v_lshlrev_b32_e32 v11, 16, v11
	v_lshlrev_b32_e32 v12, 16, v12
	v_lshlrev_b32_e32 v13, 16, v13
	v_lshlrev_b32_e32 v14, 16, v14
	v_lshlrev_b32_e32 v15, 16, v15
	v_fma_f32 v0, v178, v8, v0
	v_fma_f32 v1, v178, v9, v1
	v_fma_f32 v2, v178, v10, v2
	v_fma_f32 v3, v178, v11, v3
	v_fma_f32 v4, v178, v12, v4
	v_fma_f32 v5, v178, v13, v5
	v_fma_f32 v6, v178, v14, v6
	v_fma_f32 v7, v178, v15, v7
	v_mul_f32_e32 v198, 0x3d372713, v0
	v_mul_f32_e32 v199, 0x3d372713, v1
	v_mul_f32_e32 v200, 0x3d372713, v2
	v_mul_f32_e32 v201, 0x3d372713, v3
	v_mul_f32_e32 v202, 0x3d372713, v4
	v_mul_f32_e32 v203, 0x3d372713, v5
	v_mul_f32_e32 v204, 0x3d372713, v6
	v_mul_f32_e32 v205, 0x3d372713, v7
	v_mul_f32_e32 v198, v0, v198
	v_mul_f32_e32 v199, v1, v199
	v_mul_f32_e32 v200, v2, v200
	v_mul_f32_e32 v201, v3, v201
	v_mul_f32_e32 v202, v4, v202
	v_mul_f32_e32 v203, v5, v203
	v_mul_f32_e32 v204, v6, v204
	v_mul_f32_e32 v205, v7, v205
	v_fma_f32 v198, v0, v198, v0
	v_fma_f32 v199, v1, v199, v1
	v_fma_f32 v200, v2, v200, v2
	v_fma_f32 v201, v3, v201, v3
	v_fma_f32 v202, v4, v202, v4
	v_fma_f32 v203, v5, v203, v5
	v_fma_f32 v204, v6, v204, v6
	v_fma_f32 v205, v7, v205, v7
	v_mul_f32_e32 v198, 0x3fcc422a, v198
	v_mul_f32_e32 v199, 0x3fcc422a, v199
	v_mul_f32_e32 v200, 0x3fcc422a, v200
	v_mul_f32_e32 v201, 0x3fcc422a, v201
	v_mul_f32_e32 v202, 0x3fcc422a, v202
	v_mul_f32_e32 v203, 0x3fcc422a, v203
	v_mul_f32_e32 v204, 0x3fcc422a, v204
	v_mul_f32_e32 v205, 0x3fcc422a, v205
	v_mul_f32_e32 v198, 0xbfb8aa3b, v198
	v_mul_f32_e32 v199, 0xbfb8aa3b, v199
	v_mul_f32_e32 v200, 0xbfb8aa3b, v200
	v_mul_f32_e32 v201, 0xbfb8aa3b, v201
	v_mul_f32_e32 v202, 0xbfb8aa3b, v202
	v_mul_f32_e32 v203, 0xbfb8aa3b, v203
	v_mul_f32_e32 v204, 0xbfb8aa3b, v204
	v_mul_f32_e32 v205, 0xbfb8aa3b, v205
	v_exp_f32_e32 v198, v198
	v_exp_f32_e32 v199, v199
	v_exp_f32_e32 v200, v200
	v_exp_f32_e32 v201, v201
	v_exp_f32_e32 v202, v202
	v_exp_f32_e32 v203, v203
	v_exp_f32_e32 v204, v204
	v_exp_f32_e32 v205, v205
	v_add_f32_e32 v198, 1.0, v198
	v_add_f32_e32 v199, 1.0, v199
	v_add_f32_e32 v200, 1.0, v200
	v_add_f32_e32 v201, 1.0, v201
	v_add_f32_e32 v202, 1.0, v202
	v_add_f32_e32 v203, 1.0, v203
	v_add_f32_e32 v204, 1.0, v204
	v_add_f32_e32 v205, 1.0, v205
	v_rcp_f32_e32 v198, v198
	v_rcp_f32_e32 v199, v199
	v_rcp_f32_e32 v200, v200
	v_rcp_f32_e32 v201, v201
	v_rcp_f32_e32 v202, v202
	v_rcp_f32_e32 v203, v203
	v_rcp_f32_e32 v204, v204
	v_rcp_f32_e32 v205, v205
	v_mul_f32_e32 v0, v0, v198
	v_mul_f32_e32 v1, v1, v199
	v_mul_f32_e32 v2, v2, v200
	v_mul_f32_e32 v3, v3, v201
	v_mul_f32_e32 v4, v4, v202
	v_mul_f32_e32 v5, v5, v203
	v_mul_f32_e32 v6, v6, v204
	v_mul_f32_e32 v7, v7, v205
	v_cvt_pk_bf16_f32 v0, v0, v101
	v_cvt_pk_bf16_f32 v1, v1, v101
	v_cvt_pk_bf16_f32 v2, v2, v101
	v_cvt_pk_bf16_f32 v3, v3, v101
	v_cvt_pk_bf16_f32 v4, v4, v101
	v_cvt_pk_bf16_f32 v5, v5, v101
	v_cvt_pk_bf16_f32 v6, v6, v101
	v_cvt_pk_bf16_f32 v7, v7, v101
	ds_write_b16 v195, v0 offset:32
	ds_write_b16 v195, v1 offset:176
	ds_write_b16 v195, v2 offset:320
	ds_write_b16 v195, v3 offset:464
	ds_write_b16 v195, v4 offset:2336
	ds_write_b16 v195, v5 offset:2480
	ds_write_b16 v195, v6 offset:2624
	ds_write_b16 v195, v7 offset:2768
	s_waitcnt lgkmcnt(0)
	global_load_dwordx4 v[92:95], v[146:147], off
	global_load_dwordx4 v[88:91], v[148:149], off
	global_load_dwordx4 v[84:87], v[150:151], off
	global_load_dwordx4 v[80:83], v[152:153], off
	ds_read_b128 v[250:253], v192 offset:64
	s_waitcnt vmcnt(11) lgkmcnt(0)
	v_mfma_f32_32x32x16_bf16 v[0:15], v[250:253], v[76:79], 0
	global_load_dwordx4 v[60:63], v[154:155], off
	global_load_dwordx4 v[56:59], v[154:155], off offset:1024
	global_load_dwordx4 v[48:51], v[154:155], off offset:2048
	global_load_dwordx4 v[52:55], v[154:155], off offset:3072
	s_waitcnt vmcnt(14)
	v_mfma_f32_32x32x16_bf16 v[214:229], v[250:253], v[72:75], 0
	s_waitcnt vmcnt(13)
	v_mfma_f32_32x32x16_bf16 v[234:249], v[250:253], v[68:71], 0
	s_waitcnt vmcnt(12)
; __device__ __forceinline__ float bf_lo(unsigned w) { return __uint_as_float(w << 16); }
; __device__ __forceinline__ float bf_hi(unsigned w) { return __uint_as_float(w & 0xffff0000u); }
; #define LAS __attribute__((address_space(3)))
; #define LDS_FENCE() asm volatile("s_waitcnt lgkmcnt(0)" ::: "memory")
; __device__ __forceinline__ unsigned cvt_pk_c(float lo, float hi) { const v2f v = {lo, hi}; const bf16x2_t b = __builtin_convertvector(v, bf16x2_t); return __builtin_bit_cast(unsigned, b); }
; __device__ __forceinline__ unsigned cvt_pk_nv(float lo, float hi) { unsigned r; asm("v_cvt_pk_bf16_f32 %0, %1, %2" : "=v"(r) : "v"(lo), "v"(hi)); return r; }
; template <bool PASS2>
; __device__ __forceinline__ void s5_tile(const Ctx& C, int T, int sb_lo, int sb_hi, LAS unsigned char* lds, int wave, int lane) {
;     ...
;             for (int cb = 0; cb < 4; ++cb) {
;                 v16f acc;
; #pragma unroll
;                 for (int r = 0; r < 16; ++r) acc[r] = 0.f;
;                 acc = __builtin_amdgcn_mfma_f32_32x32x16_bf16(bb[cb], a, acc, 0, 0, 0);
; #pragma unroll
;                 for (int rg = 0; rg < 4; ++rg) { v2u w; w.x = cvt_pk_c(acc[4 * rg], acc[4 * rg + 1]); w.y = cvt_pk_c(acc[4 * rg + 2], acc[4 * rg + 3]);
;                     *(LAS v2u*)(BH + tl * BH_STRIDE + cb * 32 + 8 * rg + 4 * hh) = w; }
;             }
;             LDS_FENCE();
;             {
;                 unsigned bu[32];
; #pragma unroll
;                 for (int t = 0; t < 32; ++t) bu[t] = *(const LAS unsigned*)(BH + t * BH_STRIDE + 2 * lane);
;                 LDS_FENCE();
;                 float xr = sr[gi], xi = si[gi];
; #pragma unroll
;                 for (int t = 0; t < 32; ++t) {
;                     if (sample && t == 0) { xr = s0ar; xi = s0ai; }
;                     if (sample && t == 16) { xr = s0br; xi = s0bi; }
;                     const float nr = fmaf(lr[gi], xr, fmaf(-li[gi], xi, bf_lo(bu[t]))), ni = fmaf(lr[gi], xi, fmaf(li[gi], xr, bf_hi(bu[t])));
;                     xr = nr; xi = ni;
;                     if (PASS2) {
;                         *(LAS unsigned*)(BH + t * BH_STRIDE + 2 * lane) = cvt_pk_nv(xr, xi);
	v_mfma_f32_32x32x16_bf16 v[198:213], v[250:253], v[64:67], 0
	s_nop 11
	v_permlane32_swap_b32_e32 v0, v234
	v_permlane32_swap_b32_e32 v1, v235
	v_permlane32_swap_b32_e32 v2, v236
	v_permlane32_swap_b32_e32 v3, v237
	v_permlane32_swap_b32_e32 v4, v238
	v_permlane32_swap_b32_e32 v5, v239
	v_permlane32_swap_b32_e32 v6, v240
	v_permlane32_swap_b32_e32 v7, v241
	v_permlane32_swap_b32_e32 v8, v242
	v_permlane32_swap_b32_e32 v9, v243
	v_permlane32_swap_b32_e32 v10, v244
	v_permlane32_swap_b32_e32 v11, v245
	v_permlane32_swap_b32_e32 v12, v246
	v_permlane32_swap_b32_e32 v13, v247
	v_permlane32_swap_b32_e32 v14, v248
	v_permlane32_swap_b32_e32 v15, v249
	v_permlane32_swap_b32_e32 v214, v198
	v_permlane32_swap_b32_e32 v215, v199
	v_permlane32_swap_b32_e32 v216, v200
	v_permlane32_swap_b32_e32 v217, v201
	v_permlane32_swap_b32_e32 v218, v202
	v_permlane32_swap_b32_e32 v219, v203
	v_permlane32_swap_b32_e32 v220, v204
	v_permlane32_swap_b32_e32 v221, v205
	v_permlane32_swap_b32_e32 v222, v206
	v_permlane32_swap_b32_e32 v223, v207
	v_permlane32_swap_b32_e32 v224, v208
	v_permlane32_swap_b32_e32 v225, v209
	v_permlane32_swap_b32_e32 v226, v210
	v_permlane32_swap_b32_e32 v227, v211
	v_permlane32_swap_b32_e32 v228, v212
	v_permlane32_swap_b32_e32 v229, v213
	v_fma_f32 v0, -v180, v108, v0
	v_fma_f32 v214, v180, v110, v214
	v_fma_f32 v110, v179, v110, v0
	v_fma_f32 v108, v179, v108, v214
	v_cvt_pk_bf16_f32 v197, v110, v108
	ds_write_b32 v107, v197 offset:4608
	v_fma_f32 v1, -v180, v108, v1
	v_fma_f32 v215, v180, v110, v215
	v_fma_f32 v110, v179, v110, v1
	v_fma_f32 v108, v179, v108, v215
	v_cvt_pk_bf16_f32 v197, v110, v108
	ds_write_b32 v107, v197 offset:4880
	v_fma_f32 v2, -v180, v108, v2
	v_fma_f32 v216, v180, v110, v216
	v_fma_f32 v110, v179, v110, v2
	v_fma_f32 v108, v179, v108, v216
	v_cvt_pk_bf16_f32 v197, v110, v108
	ds_write_b32 v107, v197 offset:5152
	v_fma_f32 v3, -v180, v108, v3
	v_fma_f32 v217, v180, v110, v217
	v_fma_f32 v110, v179, v110, v3
	v_fma_f32 v108, v179, v108, v217
	v_cvt_pk_bf16_f32 v197, v110, v108
	ds_write_b32 v107, v197 offset:5424
	v_fma_f32 v234, -v180, v108, v234
	v_fma_f32 v198, v180, v110, v198
	v_fma_f32 v110, v179, v110, v234
	v_fma_f32 v108, v179, v108, v198
	v_cvt_pk_bf16_f32 v197, v110, v108
	ds_write_b32 v107, v197 offset:5696
	v_fma_f32 v235, -v180, v108, v235
	v_fma_f32 v199, v180, v110, v199
	v_fma_f32 v110, v179, v110, v235
	v_fma_f32 v108, v179, v108, v199
	v_cvt_pk_bf16_f32 v197, v110, v108
	ds_write_b32 v107, v197 offset:5968
	v_fma_f32 v236, -v180, v108, v236
	v_fma_f32 v200, v180, v110, v200
	v_fma_f32 v110, v179, v110, v236
	v_fma_f32 v108, v179, v108, v200
	v_cvt_pk_bf16_f32 v197, v110, v108
	ds_write_b32 v107, v197 offset:6240
	v_fma_f32 v237, -v180, v108, v237
	v_fma_f32 v201, v180, v110, v201
	v_fma_f32 v110, v179, v110, v237
	v_fma_f32 v108, v179, v108, v201
	v_cvt_pk_bf16_f32 v197, v110, v108
	ds_write_b32 v107, v197 offset:6512
	v_fma_f32 v4, -v180, v108, v4
	v_fma_f32 v218, v180, v110, v218
	v_fma_f32 v110, v179, v110, v4
	v_fma_f32 v108, v179, v108, v218
	v_cvt_pk_bf16_f32 v197, v110, v108
	ds_write_b32 v107, v197 offset:6784
	v_fma_f32 v5, -v180, v108, v5
	v_fma_f32 v219, v180, v110, v219
	v_fma_f32 v110, v179, v110, v5
	v_fma_f32 v108, v179, v108, v219
	v_cvt_pk_bf16_f32 v197, v110, v108
	ds_write_b32 v107, v197 offset:7056
	v_fma_f32 v6, -v180, v108, v6
	v_fma_f32 v220, v180, v110, v220
	v_fma_f32 v110, v179, v110, v6
	v_fma_f32 v108, v179, v108, v220
	v_cvt_pk_bf16_f32 v197, v110, v108
	ds_write_b32 v107, v197 offset:7328
	v_fma_f32 v7, -v180, v108, v7
	v_fma_f32 v221, v180, v110, v221
	v_fma_f32 v110, v179, v110, v7
	v_fma_f32 v108, v179, v108, v221
	v_cvt_pk_bf16_f32 v197, v110, v108
	ds_write_b32 v107, v197 offset:7600
	v_fma_f32 v238, -v180, v108, v238
	v_fma_f32 v202, v180, v110, v202
	v_fma_f32 v110, v179, v110, v238
	v_fma_f32 v108, v179, v108, v202
	v_cvt_pk_bf16_f32 v197, v110, v108
	ds_write_b32 v107, v197 offset:7872
	v_fma_f32 v239, -v180, v108, v239
	v_fma_f32 v203, v180, v110, v203
	v_fma_f32 v110, v179, v110, v239
	v_fma_f32 v108, v179, v108, v203
	v_cvt_pk_bf16_f32 v197, v110, v108
	ds_write_b32 v107, v197 offset:8144
	v_fma_f32 v240, -v180, v108, v240
	v_fma_f32 v204, v180, v110, v204
	v_fma_f32 v110, v179, v110, v240
	v_fma_f32 v108, v179, v108, v204
	v_cvt_pk_bf16_f32 v197, v110, v108
	ds_write_b32 v107, v197 offset:8416
	v_fma_f32 v241, -v180, v108, v241
	v_fma_f32 v205, v180, v110, v205
	v_fma_f32 v110, v179, v110, v241
	v_fma_f32 v108, v179, v108, v205
	v_cvt_pk_bf16_f32 v197, v110, v108
	ds_write_b32 v107, v197 offset:8688
	v_fma_f32 v8, -v180, v108, v8
	v_fma_f32 v222, v180, v110, v222
	v_fma_f32 v110, v179, v110, v8
	v_fma_f32 v108, v179, v108, v222
	v_cvt_pk_bf16_f32 v197, v110, v108
	ds_write_b32 v107, v197 offset:8960
	v_fma_f32 v9, -v180, v108, v9
	v_fma_f32 v223, v180, v110, v223
	v_fma_f32 v110, v179, v110, v9
	v_fma_f32 v108, v179, v108, v223
	v_cvt_pk_bf16_f32 v197, v110, v108
	ds_write_b32 v107, v197 offset:9232
	v_fma_f32 v10, -v180, v108, v10
	v_fma_f32 v224, v180, v110, v224
	v_fma_f32 v110, v179, v110, v10
	v_fma_f32 v108, v179, v108, v224
	v_cvt_pk_bf16_f32 v197, v110, v108
	ds_write_b32 v107, v197 offset:9504
	v_fma_f32 v11, -v180, v108, v11
	v_fma_f32 v225, v180, v110, v225
	v_fma_f32 v110, v179, v110, v11
	v_fma_f32 v108, v179, v108, v225
	v_cvt_pk_bf16_f32 v197, v110, v108
	ds_write_b32 v107, v197 offset:9776
	v_fma_f32 v242, -v180, v108, v242
	v_fma_f32 v206, v180, v110, v206
	v_fma_f32 v110, v179, v110, v242
	v_fma_f32 v108, v179, v108, v206
	v_cvt_pk_bf16_f32 v197, v110, v108
	ds_write_b32 v107, v197 offset:10048
	v_fma_f32 v243, -v180, v108, v243
; __device__ __forceinline__ float bf_lo(unsigned w) { return __uint_as_float(w << 16); }
; __device__ __forceinline__ float bf_hi(unsigned w) { return __uint_as_float(w & 0xffff0000u); }
; __device__ __forceinline__ float gelu_t(float x) { const float u = 1.5957691216057308f * (x + 0.044715f * x * x * x); return x * sigmoid_f(u); }
; #define LAS __attribute__((address_space(3)))
; #define LDS_FENCE() asm volatile("s_waitcnt lgkmcnt(0)" ::: "memory")
; __device__ __forceinline__ bf16 f2bf(float f) { return (bf16)(cvt_pk_nv(f, 0.f) & 0xffffu); }
; template <bool PASS2>
; __device__ __forceinline__ void s5_tile(const Ctx& C, int T, int sb_lo, int sb_hi, LAS unsigned char* lds, int wave, int lane) {
;     ...
;                 for (int t = 0; t < 32; ++t) {
;                     if (sample && t == 0) { xr = s0ar; xi = s0ai; }
;                     if (sample && t == 16) { xr = s0br; xi = s0bi; }
;                     const float nr = fmaf(lr[gi], xr, fmaf(-li[gi], xi, bf_lo(bu[t]))), ni = fmaf(lr[gi], xi, fmaf(li[gi], xr, bf_hi(bu[t])));
;                     xr = nr; xi = ni;
;                     if (PASS2) {
;                         *(LAS unsigned*)(BH + t * BH_STRIDE + 2 * lane) = cvt_pk_nv(xr, xi);
;                         if (sample && (t & 15) == 15) { const int seq = 2 * sb + (t >> 4);
;                             C.out()[OFF_SRE_S + ((size_t)seq * NG + g) * NP + lane] = xr; C.out()[OFF_SIM_S + ((size_t)seq * NG + g) * NP + lane] = xi; }
;                     }
;                 }
;                 sr[gi] = xr; si[gi] = xi;
;             }
;             LDS_FENCE();
;             if (PASS2) {
; #pragma unroll
;                 for (int rb = 0; rb < 2; ++rb) {
;                     v4f acc = (v4f){0.f, 0.f, 0.f, 0.f};
; #pragma unroll
;                     for (int ks = 0; ks < 4; ++ks) {
;                         const bfx8 sa = *(const LAS bfx8*)(BH + (16 * rb + fr) * BH_STRIDE + 32 * ks + 8 * kq);
;                         acc = __builtin_amdgcn_mfma_f32_16x16x32_bf16(sa, cm[ks], acc, 0, 0, 0);
;                     }
; #pragma unroll
;                     for (int r = 0; r < 4; ++r) {
;                         LAS bf16* up = XU + (16 * rb + 4 * kq + r) * XU_STRIDE + 16 * gi + fr;
;                         const float u = __uint_as_float((unsigned)(*up) << 16);
;                         *up = f2bf(gelu_t(acc[r] + dsk[gi] * u));
;                     }
	v_fma_f32 v207, v180, v110, v207
	v_fma_f32 v110, v179, v110, v243
	v_fma_f32 v108, v179, v108, v207
	v_cvt_pk_bf16_f32 v197, v110, v108
	ds_write_b32 v107, v197 offset:10320
	v_fma_f32 v244, -v180, v108, v244
	v_fma_f32 v208, v180, v110, v208
	v_fma_f32 v110, v179, v110, v244
	v_fma_f32 v108, v179, v108, v208
	v_cvt_pk_bf16_f32 v197, v110, v108
	ds_write_b32 v107, v197 offset:10592
	v_fma_f32 v245, -v180, v108, v245
	v_fma_f32 v209, v180, v110, v209
	v_fma_f32 v110, v179, v110, v245
	v_fma_f32 v108, v179, v108, v209
	v_cvt_pk_bf16_f32 v197, v110, v108
	ds_write_b32 v107, v197 offset:10864
	v_fma_f32 v12, -v180, v108, v12
	v_fma_f32 v226, v180, v110, v226
	v_fma_f32 v110, v179, v110, v12
	v_fma_f32 v108, v179, v108, v226
	v_cvt_pk_bf16_f32 v197, v110, v108
	ds_write_b32 v107, v197 offset:11136
	v_fma_f32 v13, -v180, v108, v13
	v_fma_f32 v227, v180, v110, v227
	v_fma_f32 v110, v179, v110, v13
	v_fma_f32 v108, v179, v108, v227
	v_cvt_pk_bf16_f32 v197, v110, v108
	ds_write_b32 v107, v197 offset:11408
	v_fma_f32 v14, -v180, v108, v14
	v_fma_f32 v228, v180, v110, v228
	v_fma_f32 v110, v179, v110, v14
	v_fma_f32 v108, v179, v108, v228
	v_cvt_pk_bf16_f32 v197, v110, v108
	ds_write_b32 v107, v197 offset:11680
	v_fma_f32 v15, -v180, v108, v15
	v_fma_f32 v229, v180, v110, v229
	v_fma_f32 v110, v179, v110, v15
	v_fma_f32 v108, v179, v108, v229
	v_cvt_pk_bf16_f32 v197, v110, v108
	ds_write_b32 v107, v197 offset:11952
	v_fma_f32 v246, -v180, v108, v246
	v_fma_f32 v210, v180, v110, v210
	v_fma_f32 v110, v179, v110, v246
	v_fma_f32 v108, v179, v108, v210
	v_cvt_pk_bf16_f32 v197, v110, v108
	ds_write_b32 v107, v197 offset:12224
	v_fma_f32 v247, -v180, v108, v247
	v_fma_f32 v211, v180, v110, v211
	v_fma_f32 v110, v179, v110, v247
	v_fma_f32 v108, v179, v108, v211
	v_cvt_pk_bf16_f32 v197, v110, v108
	ds_write_b32 v107, v197 offset:12496
	v_fma_f32 v248, -v180, v108, v248
	v_fma_f32 v212, v180, v110, v212
	v_fma_f32 v110, v179, v110, v248
	v_fma_f32 v108, v179, v108, v212
	v_cvt_pk_bf16_f32 v197, v110, v108
	ds_write_b32 v107, v197 offset:12768
	v_fma_f32 v249, -v180, v108, v249
	v_fma_f32 v213, v180, v110, v213
	v_fma_f32 v110, v179, v110, v249
	v_fma_f32 v108, v179, v108, v213
	v_cvt_pk_bf16_f32 v197, v110, v108
	ds_write_b32 v107, v197 offset:13040
	s_waitcnt lgkmcnt(0)
	ds_read_b128 v[214:217], v194 offset:4608
	ds_read_b128 v[218:221], v194 offset:4672
	ds_read_b128 v[222:225], v194 offset:4736
	ds_read_b128 v[226:229], v194 offset:4800
	ds_read_b128 v[234:237], v194 offset:8960
	ds_read_b128 v[238:241], v194 offset:9024
	ds_read_b128 v[242:245], v194 offset:9088
	ds_read_b128 v[246:249], v194 offset:9152
	ds_read_u16 v8, v195 offset:64
	ds_read_u16 v9, v195 offset:208
	ds_read_u16 v10, v195 offset:352
	ds_read_u16 v11, v195 offset:496
	ds_read_u16 v12, v195 offset:2368
	ds_read_u16 v13, v195 offset:2512
	ds_read_u16 v14, v195 offset:2656
	ds_read_u16 v15, v195 offset:2800
	s_waitcnt vmcnt(8) lgkmcnt(8)
	v_mfma_f32_16x16x32_bf16 v[0:3], v[214:217], v[44:47], 0
	v_mfma_f32_16x16x32_bf16 v[4:7], v[234:237], v[44:47], 0
	v_mfma_f32_16x16x32_bf16 v[0:3], v[218:221], v[40:43], v[0:3]
	v_mfma_f32_16x16x32_bf16 v[4:7], v[238:241], v[40:43], v[4:7]
	v_mfma_f32_16x16x32_bf16 v[0:3], v[222:225], v[32:35], v[0:3]
	v_mfma_f32_16x16x32_bf16 v[4:7], v[242:245], v[32:35], v[4:7]
	v_mfma_f32_16x16x32_bf16 v[0:3], v[226:229], v[36:39], v[0:3]
	v_mfma_f32_16x16x32_bf16 v[4:7], v[246:249], v[36:39], v[4:7]
	s_waitcnt lgkmcnt(0)
	v_lshlrev_b32_e32 v8, 16, v8
	v_lshlrev_b32_e32 v9, 16, v9
	v_lshlrev_b32_e32 v10, 16, v10
	v_lshlrev_b32_e32 v11, 16, v11
	v_lshlrev_b32_e32 v12, 16, v12
	v_lshlrev_b32_e32 v13, 16, v13
	v_lshlrev_b32_e32 v14, 16, v14
	v_lshlrev_b32_e32 v15, 16, v15
	v_fma_f32 v0, v181, v8, v0
	v_fma_f32 v1, v181, v9, v1
	v_fma_f32 v2, v181, v10, v2
	v_fma_f32 v3, v181, v11, v3
	v_fma_f32 v4, v181, v12, v4
	v_fma_f32 v5, v181, v13, v5
	v_fma_f32 v6, v181, v14, v6
	v_fma_f32 v7, v181, v15, v7
	v_mul_f32_e32 v198, 0x3d372713, v0
	v_mul_f32_e32 v199, 0x3d372713, v1
	v_mul_f32_e32 v200, 0x3d372713, v2
	v_mul_f32_e32 v201, 0x3d372713, v3
	v_mul_f32_e32 v202, 0x3d372713, v4
	v_mul_f32_e32 v203, 0x3d372713, v5
	v_mul_f32_e32 v204, 0x3d372713, v6
	v_mul_f32_e32 v205, 0x3d372713, v7
	v_mul_f32_e32 v198, v0, v198
	v_mul_f32_e32 v199, v1, v199
	v_mul_f32_e32 v200, v2, v200
	v_mul_f32_e32 v201, v3, v201
	v_mul_f32_e32 v202, v4, v202
	v_mul_f32_e32 v203, v5, v203
	v_mul_f32_e32 v204, v6, v204
	v_mul_f32_e32 v205, v7, v205
	v_fma_f32 v198, v0, v198, v0
	v_fma_f32 v199, v1, v199, v1
	v_fma_f32 v200, v2, v200, v2
	v_fma_f32 v201, v3, v201, v3
	v_fma_f32 v202, v4, v202, v4
	v_fma_f32 v203, v5, v203, v5
	v_fma_f32 v204, v6, v204, v6
	v_fma_f32 v205, v7, v205, v7
	v_mul_f32_e32 v198, 0x3fcc422a, v198
	v_mul_f32_e32 v199, 0x3fcc422a, v199
	v_mul_f32_e32 v200, 0x3fcc422a, v200
	v_mul_f32_e32 v201, 0x3fcc422a, v201
	v_mul_f32_e32 v202, 0x3fcc422a, v202
	v_mul_f32_e32 v203, 0x3fcc422a, v203
	v_mul_f32_e32 v204, 0x3fcc422a, v204
	v_mul_f32_e32 v205, 0x3fcc422a, v205
	v_mul_f32_e32 v198, 0xbfb8aa3b, v198
	v_mul_f32_e32 v199, 0xbfb8aa3b, v199
	v_mul_f32_e32 v200, 0xbfb8aa3b, v200
	v_mul_f32_e32 v201, 0xbfb8aa3b, v201
	v_mul_f32_e32 v202, 0xbfb8aa3b, v202
	v_mul_f32_e32 v203, 0xbfb8aa3b, v203
	v_mul_f32_e32 v204, 0xbfb8aa3b, v204
	v_mul_f32_e32 v205, 0xbfb8aa3b, v205
	v_exp_f32_e32 v198, v198
	v_exp_f32_e32 v199, v199
	v_exp_f32_e32 v200, v200
	v_exp_f32_e32 v201, v201
	v_exp_f32_e32 v202, v202
	v_exp_f32_e32 v203, v203
	v_exp_f32_e32 v204, v204
	v_exp_f32_e32 v205, v205
	v_add_f32_e32 v198, 1.0, v198
	v_add_f32_e32 v199, 1.0, v199
	v_add_f32_e32 v200, 1.0, v200
	v_add_f32_e32 v201, 1.0, v201
	v_add_f32_e32 v202, 1.0, v202
	v_add_f32_e32 v203, 1.0, v203
	v_add_f32_e32 v204, 1.0, v204
	v_add_f32_e32 v205, 1.0, v205
	v_rcp_f32_e32 v198, v198
	v_rcp_f32_e32 v199, v199
	v_rcp_f32_e32 v200, v200
	v_rcp_f32_e32 v201, v201
	v_rcp_f32_e32 v202, v202
	v_rcp_f32_e32 v203, v203
	v_rcp_f32_e32 v204, v204
	v_rcp_f32_e32 v205, v205
	v_mul_f32_e32 v0, v0, v198
	v_mul_f32_e32 v1, v1, v199
	v_mul_f32_e32 v2, v2, v200
	v_mul_f32_e32 v3, v3, v201
	v_mul_f32_e32 v4, v4, v202
	v_mul_f32_e32 v5, v5, v203
	v_mul_f32_e32 v6, v6, v204
	v_mul_f32_e32 v7, v7, v205
	v_cvt_pk_bf16_f32 v0, v0, v101
	v_cvt_pk_bf16_f32 v1, v1, v101
	v_cvt_pk_bf16_f32 v2, v2, v101
	v_cvt_pk_bf16_f32 v3, v3, v101
	v_cvt_pk_bf16_f32 v4, v4, v101
	v_cvt_pk_bf16_f32 v5, v5, v101
	v_cvt_pk_bf16_f32 v6, v6, v101
	v_cvt_pk_bf16_f32 v7, v7, v101
	ds_write_b16 v195, v0 offset:64
	ds_write_b16 v195, v1 offset:208
	ds_write_b16 v195, v2 offset:352
	ds_write_b16 v195, v3 offset:496
	ds_write_b16 v195, v4 offset:2368
	ds_write_b16 v195, v5 offset:2512
	ds_write_b16 v195, v6 offset:2656
	ds_write_b16 v195, v7 offset:2800
	s_waitcnt lgkmcnt(0)
; #define LAS __attribute__((address_space(3)))
; template <bool PASS2>
; __device__ __forceinline__ void s5_tile(const Ctx& C, int T, int sb_lo, int sb_hi, LAS unsigned char* lds, int wave, int lane) {
;     ...
;         for (int gi = 0; gi < 4; ++gi) {
;             const int g = wave * 4 + gi, gnx = wave * 4 + ((gi + 1) & 3);
;             bfx8 bb[4], cm[4];
; #pragma unroll
;             for (int cb = 0; cb < 4; ++cb) { bb[cb] = bbn[cb]; bbn[cb] = *(const bfx8*)(BBt + ((size_t)(gnx * 128 + cb * 32 + tl)) * GN + 8 * hh); }
;             if (PASS2) {
; #pragma unroll
;                 for (int ks = 0; ks < 4; ++ks) { cm[ks] = cmn[ks]; cmn[ks] = *(const bfx8*)(CMt + ((size_t)(gnx * GN + fr)) * 128 + 32 * ks + 8 * kq); }
;             }
;             float s0ar = 0.f, s0ai = 0.f, s0br = 0.f, s0bi = 0.f;
;             if (sample) { const size_t o0 = ((size_t)(2 * sb) * NG + g) * NP + lane, o1 = o0 + (size_t)NG * NP;
;                 s0ar = C.in(2)[o0]; s0ai = C.in(3)[o0]; s0br = C.in(2)[o1]; s0bi = C.in(3)[o1]; }
;             const bfx8 a = *(const LAS bfx8*)(XU + tl * XU_STRIDE + 16 * gi + 8 * hh);
; #pragma unroll
;             for (int cb = 0; cb < 4; ++cb) {
;                 v16f acc;
; #pragma unroll
;                 for (int r = 0; r < 16; ++r) acc[r] = 0.f;
;                 acc = __builtin_amdgcn_mfma_f32_32x32x16_bf16(bb[cb], a, acc, 0, 0, 0);
; #pragma unroll
;                 for (int rg = 0; rg < 4; ++rg) { v2u w; w.x = cvt_pk_c(acc[4 * rg], acc[4 * rg + 1]); w.y = cvt_pk_c(acc[4 * rg + 2], acc[4 * rg + 3]);
;                     *(LAS v2u*)(BH + tl * BH_STRIDE + cb * 32 + 8 * rg + 4 * hh) = w; }
;             }
;             LDS_FENCE();
;             {
;                 unsigned bu[32];
; #pragma unroll
;                 for (int t = 0; t < 32; ++t) bu[t] = *(const LAS unsigned*)(BH + t * BH_STRIDE + 2 * lane);
;                 LDS_FENCE();
;                 float xr = sr[gi], xi = si[gi];
; #pragma unroll
;                 for (int t = 0; t < 32; ++t) {
;                     if (sample && t == 0) { xr = s0ar; xi = s0ai; }
;                     if (sample && t == 16) { xr = s0br; xi = s0bi; }
;                     const float nr = fmaf(lr[gi], xr, fmaf(-li[gi], xi, bf_lo(bu[t]))), ni = fmaf(lr[gi], xi, fmaf(li[gi], xr, bf_hi(bu[t])));
;                     xr = nr; xi = ni;
;                     if (PASS2) {
	global_load_dwordx4 v[76:79], v[124:125], off
	global_load_dwordx4 v[72:75], v[122:123], off
	global_load_dwordx4 v[68:71], v[120:121], off
	global_load_dwordx4 v[64:67], v[118:119], off
	ds_read_b128 v[250:253], v192 offset:96
	s_waitcnt vmcnt(11) lgkmcnt(0)
	v_mfma_f32_32x32x16_bf16 v[0:15], v[250:253], v[92:95], 0
	global_load_dwordx4 v[44:47], v[156:157], off
	global_load_dwordx4 v[40:43], v[156:157], off offset:1024
	global_load_dwordx4 v[36:39], v[156:157], off offset:2048
	global_load_dwordx4 v[32:35], v[156:157], off offset:3072
	s_waitcnt vmcnt(14)
	v_mfma_f32_32x32x16_bf16 v[214:229], v[250:253], v[88:91], 0
	s_waitcnt vmcnt(13)
	v_mfma_f32_32x32x16_bf16 v[234:249], v[250:253], v[84:87], 0
	s_waitcnt vmcnt(12)
	v_mfma_f32_32x32x16_bf16 v[198:213], v[250:253], v[80:83], 0
	s_nop 11
	v_permlane32_swap_b32_e32 v0, v234
	v_permlane32_swap_b32_e32 v1, v235
	v_permlane32_swap_b32_e32 v2, v236
	v_permlane32_swap_b32_e32 v3, v237
	v_permlane32_swap_b32_e32 v4, v238
	v_permlane32_swap_b32_e32 v5, v239
	v_permlane32_swap_b32_e32 v6, v240
	v_permlane32_swap_b32_e32 v7, v241
	v_permlane32_swap_b32_e32 v8, v242
	v_permlane32_swap_b32_e32 v9, v243
	v_permlane32_swap_b32_e32 v10, v244
	v_permlane32_swap_b32_e32 v11, v245
	v_permlane32_swap_b32_e32 v12, v246
	v_permlane32_swap_b32_e32 v13, v247
	v_permlane32_swap_b32_e32 v14, v248
	v_permlane32_swap_b32_e32 v15, v249
	v_permlane32_swap_b32_e32 v214, v198
	v_permlane32_swap_b32_e32 v215, v199
	v_permlane32_swap_b32_e32 v216, v200
	v_permlane32_swap_b32_e32 v217, v201
	v_permlane32_swap_b32_e32 v218, v202
	v_permlane32_swap_b32_e32 v219, v203
	v_permlane32_swap_b32_e32 v220, v204
	v_permlane32_swap_b32_e32 v221, v205
	v_permlane32_swap_b32_e32 v222, v206
	v_permlane32_swap_b32_e32 v223, v207
	v_permlane32_swap_b32_e32 v224, v208
	v_permlane32_swap_b32_e32 v225, v209
	v_permlane32_swap_b32_e32 v226, v210
	v_permlane32_swap_b32_e32 v227, v211
	v_permlane32_swap_b32_e32 v228, v212
	v_permlane32_swap_b32_e32 v229, v213
	v_fma_f32 v0, -v190, v109, v0
	v_fma_f32 v214, v190, v111, v214
	v_fma_f32 v111, v189, v111, v0
	v_fma_f32 v109, v189, v109, v214
	v_cvt_pk_bf16_f32 v197, v111, v109
	ds_write_b32 v107, v197 offset:4608
	v_fma_f32 v1, -v190, v109, v1
	v_fma_f32 v215, v190, v111, v215
	v_fma_f32 v111, v189, v111, v1
	v_fma_f32 v109, v189, v109, v215
	v_cvt_pk_bf16_f32 v197, v111, v109
	ds_write_b32 v107, v197 offset:4880
	v_fma_f32 v2, -v190, v109, v2
	v_fma_f32 v216, v190, v111, v216
	v_fma_f32 v111, v189, v111, v2
	v_fma_f32 v109, v189, v109, v216
	v_cvt_pk_bf16_f32 v197, v111, v109
	ds_write_b32 v107, v197 offset:5152
	v_fma_f32 v3, -v190, v109, v3
	v_fma_f32 v217, v190, v111, v217
	v_fma_f32 v111, v189, v111, v3
	v_fma_f32 v109, v189, v109, v217
	v_cvt_pk_bf16_f32 v197, v111, v109
	ds_write_b32 v107, v197 offset:5424
	v_fma_f32 v234, -v190, v109, v234
	v_fma_f32 v198, v190, v111, v198
	v_fma_f32 v111, v189, v111, v234
	v_fma_f32 v109, v189, v109, v198
	v_cvt_pk_bf16_f32 v197, v111, v109
	ds_write_b32 v107, v197 offset:5696
	v_fma_f32 v235, -v190, v109, v235
	v_fma_f32 v199, v190, v111, v199
	v_fma_f32 v111, v189, v111, v235
	v_fma_f32 v109, v189, v109, v199
	v_cvt_pk_bf16_f32 v197, v111, v109
	ds_write_b32 v107, v197 offset:5968
	v_fma_f32 v236, -v190, v109, v236
	v_fma_f32 v200, v190, v111, v200
	v_fma_f32 v111, v189, v111, v236
	v_fma_f32 v109, v189, v109, v200
	v_cvt_pk_bf16_f32 v197, v111, v109
	ds_write_b32 v107, v197 offset:6240
	v_fma_f32 v237, -v190, v109, v237
	v_fma_f32 v201, v190, v111, v201
	v_fma_f32 v111, v189, v111, v237
	v_fma_f32 v109, v189, v109, v201
	v_cvt_pk_bf16_f32 v197, v111, v109
	ds_write_b32 v107, v197 offset:6512
	v_fma_f32 v4, -v190, v109, v4
	v_fma_f32 v218, v190, v111, v218
	v_fma_f32 v111, v189, v111, v4
	v_fma_f32 v109, v189, v109, v218
	v_cvt_pk_bf16_f32 v197, v111, v109
	ds_write_b32 v107, v197 offset:6784
	v_fma_f32 v5, -v190, v109, v5
	v_fma_f32 v219, v190, v111, v219
	v_fma_f32 v111, v189, v111, v5
	v_fma_f32 v109, v189, v109, v219
	v_cvt_pk_bf16_f32 v197, v111, v109
	ds_write_b32 v107, v197 offset:7056
	v_fma_f32 v6, -v190, v109, v6
	v_fma_f32 v220, v190, v111, v220
	v_fma_f32 v111, v189, v111, v6
	v_fma_f32 v109, v189, v109, v220
	v_cvt_pk_bf16_f32 v197, v111, v109
	ds_write_b32 v107, v197 offset:7328
	v_fma_f32 v7, -v190, v109, v7
	v_fma_f32 v221, v190, v111, v221
	v_fma_f32 v111, v189, v111, v7
	v_fma_f32 v109, v189, v109, v221
	v_cvt_pk_bf16_f32 v197, v111, v109
	ds_write_b32 v107, v197 offset:7600
	v_fma_f32 v238, -v190, v109, v238
	v_fma_f32 v202, v190, v111, v202
	v_fma_f32 v111, v189, v111, v238
	v_fma_f32 v109, v189, v109, v202
	v_cvt_pk_bf16_f32 v197, v111, v109
	ds_write_b32 v107, v197 offset:7872
	v_fma_f32 v239, -v190, v109, v239
	v_fma_f32 v203, v190, v111, v203
	v_fma_f32 v111, v189, v111, v239
	v_fma_f32 v109, v189, v109, v203
	v_cvt_pk_bf16_f32 v197, v111, v109
	ds_write_b32 v107, v197 offset:8144
	v_fma_f32 v240, -v190, v109, v240
	v_fma_f32 v204, v190, v111, v204
	v_fma_f32 v111, v189, v111, v240
	v_fma_f32 v109, v189, v109, v204
	v_cvt_pk_bf16_f32 v197, v111, v109
	ds_write_b32 v107, v197 offset:8416
	v_fma_f32 v241, -v190, v109, v241
	v_fma_f32 v205, v190, v111, v205
	v_fma_f32 v111, v189, v111, v241
	v_fma_f32 v109, v189, v109, v205
	v_cvt_pk_bf16_f32 v197, v111, v109
	ds_write_b32 v107, v197 offset:8688
	v_fma_f32 v8, -v190, v109, v8
	v_fma_f32 v222, v190, v111, v222
	v_fma_f32 v111, v189, v111, v8
	v_fma_f32 v109, v189, v109, v222
	v_cvt_pk_bf16_f32 v197, v111, v109
	ds_write_b32 v107, v197 offset:8960
	v_fma_f32 v9, -v190, v109, v9
	v_fma_f32 v223, v190, v111, v223
	v_fma_f32 v111, v189, v111, v9
	v_fma_f32 v109, v189, v109, v223
; __device__ __forceinline__ float bf_lo(unsigned w) { return __uint_as_float(w << 16); }
; __device__ __forceinline__ float bf_hi(unsigned w) { return __uint_as_float(w & 0xffff0000u); }
; #define LAS __attribute__((address_space(3)))
; #define LDS_FENCE() asm volatile("s_waitcnt lgkmcnt(0)" ::: "memory")
; __device__ __forceinline__ unsigned cvt_pk_nv(float lo, float hi) { unsigned r; asm("v_cvt_pk_bf16_f32 %0, %1, %2" : "=v"(r) : "v"(lo), "v"(hi)); return r; }
;     __device__ __forceinline__ float* out() const { return (float*)karg_in(33); }
; template <bool PASS2>
; __device__ __forceinline__ void s5_tile(const Ctx& C, int T, int sb_lo, int sb_hi, LAS unsigned char* lds, int wave, int lane) {
;     ...
;                 for (int t = 0; t < 32; ++t) {
;                     if (sample && t == 0) { xr = s0ar; xi = s0ai; }
;                     if (sample && t == 16) { xr = s0br; xi = s0bi; }
;                     const float nr = fmaf(lr[gi], xr, fmaf(-li[gi], xi, bf_lo(bu[t]))), ni = fmaf(lr[gi], xi, fmaf(li[gi], xr, bf_hi(bu[t])));
;                     xr = nr; xi = ni;
;                     if (PASS2) {
;                         *(LAS unsigned*)(BH + t * BH_STRIDE + 2 * lane) = cvt_pk_nv(xr, xi);
;                         if (sample && (t & 15) == 15) { const int seq = 2 * sb + (t >> 4);
;                             C.out()[OFF_SRE_S + ((size_t)seq * NG + g) * NP + lane] = xr; C.out()[OFF_SIM_S + ((size_t)seq * NG + g) * NP + lane] = xi; }
;                     }
;                 }
;                 sr[gi] = xr; si[gi] = xi;
;             }
;             LDS_FENCE();
;             if (PASS2) {
; #pragma unroll
;                 for (int rb = 0; rb < 2; ++rb) {
;                     v4f acc = (v4f){0.f, 0.f, 0.f, 0.f};
; #pragma unroll
;                     for (int ks = 0; ks < 4; ++ks) {
;                         const bfx8 sa = *(const LAS bfx8*)(BH + (16 * rb + fr) * BH_STRIDE + 32 * ks + 8 * kq);
;                         acc = __builtin_amdgcn_mfma_f32_16x16x32_bf16(sa, cm[ks], acc, 0, 0, 0);
;                     }
	v_cvt_pk_bf16_f32 v197, v111, v109
	ds_write_b32 v107, v197 offset:9232
	v_fma_f32 v10, -v190, v109, v10
	v_fma_f32 v224, v190, v111, v224
	v_fma_f32 v111, v189, v111, v10
	v_fma_f32 v109, v189, v109, v224
	v_cvt_pk_bf16_f32 v197, v111, v109
	ds_write_b32 v107, v197 offset:9504
	v_fma_f32 v11, -v190, v109, v11
	v_fma_f32 v225, v190, v111, v225
	v_fma_f32 v111, v189, v111, v11
	v_fma_f32 v109, v189, v109, v225
	v_cvt_pk_bf16_f32 v197, v111, v109
	ds_write_b32 v107, v197 offset:9776
	v_fma_f32 v242, -v190, v109, v242
	v_fma_f32 v206, v190, v111, v206
	v_fma_f32 v111, v189, v111, v242
	v_fma_f32 v109, v189, v109, v206
	v_cvt_pk_bf16_f32 v197, v111, v109
	ds_write_b32 v107, v197 offset:10048
	v_fma_f32 v243, -v190, v109, v243
	v_fma_f32 v207, v190, v111, v207
	v_fma_f32 v111, v189, v111, v243
	v_fma_f32 v109, v189, v109, v207
	v_cvt_pk_bf16_f32 v197, v111, v109
	ds_write_b32 v107, v197 offset:10320
	v_fma_f32 v244, -v190, v109, v244
	v_fma_f32 v208, v190, v111, v208
	v_fma_f32 v111, v189, v111, v244
	v_fma_f32 v109, v189, v109, v208
	v_cvt_pk_bf16_f32 v197, v111, v109
	ds_write_b32 v107, v197 offset:10592
	v_fma_f32 v245, -v190, v109, v245
	v_fma_f32 v209, v190, v111, v209
	v_fma_f32 v111, v189, v111, v245
	v_fma_f32 v109, v189, v109, v209
	v_cvt_pk_bf16_f32 v197, v111, v109
	ds_write_b32 v107, v197 offset:10864
	v_fma_f32 v12, -v190, v109, v12
	v_fma_f32 v226, v190, v111, v226
	v_fma_f32 v111, v189, v111, v12
	v_fma_f32 v109, v189, v109, v226
	v_cvt_pk_bf16_f32 v197, v111, v109
	ds_write_b32 v107, v197 offset:11136
	v_fma_f32 v13, -v190, v109, v13
	v_fma_f32 v227, v190, v111, v227
	v_fma_f32 v111, v189, v111, v13
	v_fma_f32 v109, v189, v109, v227
	v_cvt_pk_bf16_f32 v197, v111, v109
	ds_write_b32 v107, v197 offset:11408
	v_fma_f32 v14, -v190, v109, v14
	v_fma_f32 v228, v190, v111, v228
	v_fma_f32 v111, v189, v111, v14
	v_fma_f32 v109, v189, v109, v228
	v_cvt_pk_bf16_f32 v197, v111, v109
	ds_write_b32 v107, v197 offset:11680
	v_fma_f32 v15, -v190, v109, v15
	v_fma_f32 v229, v190, v111, v229
	v_fma_f32 v111, v189, v111, v15
	v_fma_f32 v109, v189, v109, v229
	v_cvt_pk_bf16_f32 v197, v111, v109
	ds_write_b32 v107, v197 offset:11952
	v_fma_f32 v246, -v190, v109, v246
	v_fma_f32 v210, v190, v111, v210
	v_fma_f32 v111, v189, v111, v246
	v_fma_f32 v109, v189, v109, v210
	v_cvt_pk_bf16_f32 v197, v111, v109
	ds_write_b32 v107, v197 offset:12224
	v_fma_f32 v247, -v190, v109, v247
	v_fma_f32 v211, v190, v111, v211
	v_fma_f32 v111, v189, v111, v247
	v_fma_f32 v109, v189, v109, v211
	v_cvt_pk_bf16_f32 v197, v111, v109
	ds_write_b32 v107, v197 offset:12496
	v_fma_f32 v248, -v190, v109, v248
	v_fma_f32 v212, v190, v111, v212
	v_fma_f32 v111, v189, v111, v248
	v_fma_f32 v109, v189, v109, v212
	v_cvt_pk_bf16_f32 v197, v111, v109
	ds_write_b32 v107, v197 offset:12768
	v_fma_f32 v249, -v190, v109, v249
	v_fma_f32 v213, v190, v111, v213
	v_fma_f32 v111, v189, v111, v249
	v_fma_f32 v109, v189, v109, v213
	v_cvt_pk_bf16_f32 v197, v111, v109
	ds_write_b32 v107, v197 offset:13040
	s_waitcnt lgkmcnt(0)
	ds_read_b128 v[214:217], v194 offset:4608
	ds_read_b128 v[218:221], v194 offset:4672
	ds_read_b128 v[222:225], v194 offset:4736
	ds_read_b128 v[226:229], v194 offset:4800
	ds_read_b128 v[234:237], v194 offset:8960
	ds_read_b128 v[238:241], v194 offset:9024
	ds_read_b128 v[242:245], v194 offset:9088
	ds_read_b128 v[246:249], v194 offset:9152
	ds_read_u16 v8, v195 offset:96
	ds_read_u16 v9, v195 offset:240
	ds_read_u16 v10, v195 offset:384
	ds_read_u16 v11, v195 offset:528
	ds_read_u16 v12, v195 offset:2400
	ds_read_u16 v13, v195 offset:2544
	ds_read_u16 v14, v195 offset:2688
	ds_read_u16 v15, v195 offset:2832
	s_waitcnt vmcnt(8) lgkmcnt(8)
	v_mfma_f32_16x16x32_bf16 v[0:3], v[214:217], v[60:63], 0
	v_mfma_f32_16x16x32_bf16 v[4:7], v[234:237], v[60:63], 0
	v_mfma_f32_16x16x32_bf16 v[0:3], v[218:221], v[56:59], v[0:3]
	v_mfma_f32_16x16x32_bf16 v[4:7], v[238:241], v[56:59], v[4:7]
	v_mfma_f32_16x16x32_bf16 v[0:3], v[222:225], v[48:51], v[0:3]
	v_mfma_f32_16x16x32_bf16 v[4:7], v[242:245], v[48:51], v[4:7]
	v_mfma_f32_16x16x32_bf16 v[0:3], v[226:229], v[52:55], v[0:3]
	v_mfma_f32_16x16x32_bf16 v[4:7], v[246:249], v[52:55], v[4:7]
	s_waitcnt lgkmcnt(0)
; __device__ __forceinline__ float gelu_t(float x) { const float u = 1.5957691216057308f * (x + 0.044715f * x * x * x); return x * sigmoid_f(u); }
; #define LAS __attribute__((address_space(3)))
; #define LDS_FENCE() asm volatile("s_waitcnt lgkmcnt(0)" ::: "memory")
; __device__ __forceinline__ bf16 f2bf(float f) { return (bf16)(cvt_pk_nv(f, 0.f) & 0xffffu); }
; template <bool PASS2>
; __device__ __forceinline__ void s5_tile(const Ctx& C, int T, int sb_lo, int sb_hi, LAS unsigned char* lds, int wave, int lane) {
;     ...
; #pragma unroll
;                     for (int r = 0; r < 4; ++r) {
;                         LAS bf16* up = XU + (16 * rb + 4 * kq + r) * XU_STRIDE + 16 * gi + fr;
;                         const float u = __uint_as_float((unsigned)(*up) << 16);
;                         *up = f2bf(gelu_t(acc[r] + dsk[gi] * u));
;                     }
;                 }
;                 LDS_FENCE();
;             }
;         }
;         if (PASS2) {
; #pragma unroll
;             for (int i = 0; i < 4; ++i) *(v4u*)(C.YB() + (size_t)(rb0 + xrow + 8 * i) * BWD + 64 * wave + 8 * xpart) = *(const LAS v4u*)(XU + (xrow + 8 * i) * XU_STRIDE + 8 * xpart);
;             LDS_FENCE();
;         }
;     }
	v_lshlrev_b32_e32 v8, 16, v8
	v_lshlrev_b32_e32 v9, 16, v9
	v_lshlrev_b32_e32 v10, 16, v10
	v_lshlrev_b32_e32 v11, 16, v11
	v_lshlrev_b32_e32 v12, 16, v12
	v_lshlrev_b32_e32 v13, 16, v13
	v_lshlrev_b32_e32 v14, 16, v14
	v_lshlrev_b32_e32 v15, 16, v15
	v_fma_f32 v0, v191, v8, v0
	v_fma_f32 v1, v191, v9, v1
	v_fma_f32 v2, v191, v10, v2
	v_fma_f32 v3, v191, v11, v3
	v_fma_f32 v4, v191, v12, v4
	v_fma_f32 v5, v191, v13, v5
	v_fma_f32 v6, v191, v14, v6
	v_fma_f32 v7, v191, v15, v7
	v_mul_f32_e32 v198, 0x3d372713, v0
	v_mul_f32_e32 v199, 0x3d372713, v1
	v_mul_f32_e32 v200, 0x3d372713, v2
	v_mul_f32_e32 v201, 0x3d372713, v3
	v_mul_f32_e32 v202, 0x3d372713, v4
	v_mul_f32_e32 v203, 0x3d372713, v5
	v_mul_f32_e32 v204, 0x3d372713, v6
	v_mul_f32_e32 v205, 0x3d372713, v7
	v_mul_f32_e32 v198, v0, v198
	v_mul_f32_e32 v199, v1, v199
	v_mul_f32_e32 v200, v2, v200
	v_mul_f32_e32 v201, v3, v201
	v_mul_f32_e32 v202, v4, v202
	v_mul_f32_e32 v203, v5, v203
	v_mul_f32_e32 v204, v6, v204
	v_mul_f32_e32 v205, v7, v205
	v_fma_f32 v198, v0, v198, v0
	v_fma_f32 v199, v1, v199, v1
	v_fma_f32 v200, v2, v200, v2
	v_fma_f32 v201, v3, v201, v3
	v_fma_f32 v202, v4, v202, v4
	v_fma_f32 v203, v5, v203, v5
	v_fma_f32 v204, v6, v204, v6
	v_fma_f32 v205, v7, v205, v7
	v_mul_f32_e32 v198, 0x3fcc422a, v198
	v_mul_f32_e32 v199, 0x3fcc422a, v199
	v_mul_f32_e32 v200, 0x3fcc422a, v200
	v_mul_f32_e32 v201, 0x3fcc422a, v201
	v_mul_f32_e32 v202, 0x3fcc422a, v202
	v_mul_f32_e32 v203, 0x3fcc422a, v203
	v_mul_f32_e32 v204, 0x3fcc422a, v204
	v_mul_f32_e32 v205, 0x3fcc422a, v205
	v_mul_f32_e32 v198, 0xbfb8aa3b, v198
	v_mul_f32_e32 v199, 0xbfb8aa3b, v199
	v_mul_f32_e32 v200, 0xbfb8aa3b, v200
	v_mul_f32_e32 v201, 0xbfb8aa3b, v201
	v_mul_f32_e32 v202, 0xbfb8aa3b, v202
	v_mul_f32_e32 v203, 0xbfb8aa3b, v203
	v_mul_f32_e32 v204, 0xbfb8aa3b, v204
	v_mul_f32_e32 v205, 0xbfb8aa3b, v205
	v_exp_f32_e32 v198, v198
	v_exp_f32_e32 v199, v199
	v_exp_f32_e32 v200, v200
	v_exp_f32_e32 v201, v201
	v_exp_f32_e32 v202, v202
	v_exp_f32_e32 v203, v203
	v_exp_f32_e32 v204, v204
	v_exp_f32_e32 v205, v205
	v_add_f32_e32 v198, 1.0, v198
	v_add_f32_e32 v199, 1.0, v199
	v_add_f32_e32 v200, 1.0, v200
	v_add_f32_e32 v201, 1.0, v201
	v_add_f32_e32 v202, 1.0, v202
	v_add_f32_e32 v203, 1.0, v203
	v_add_f32_e32 v204, 1.0, v204
	v_add_f32_e32 v205, 1.0, v205
	v_rcp_f32_e32 v198, v198
	v_rcp_f32_e32 v199, v199
	v_rcp_f32_e32 v200, v200
	v_rcp_f32_e32 v201, v201
	v_rcp_f32_e32 v202, v202
	v_rcp_f32_e32 v203, v203
	v_rcp_f32_e32 v204, v204
	v_rcp_f32_e32 v205, v205
	v_mul_f32_e32 v0, v0, v198
	v_mul_f32_e32 v1, v1, v199
	v_mul_f32_e32 v2, v2, v200
	v_mul_f32_e32 v3, v3, v201
	v_mul_f32_e32 v4, v4, v202
	v_mul_f32_e32 v5, v5, v203
	v_mul_f32_e32 v6, v6, v204
	v_mul_f32_e32 v7, v7, v205
	v_cvt_pk_bf16_f32 v0, v0, v101
	v_cvt_pk_bf16_f32 v1, v1, v101
	v_cvt_pk_bf16_f32 v2, v2, v101
	v_cvt_pk_bf16_f32 v3, v3, v101
	v_cvt_pk_bf16_f32 v4, v4, v101
	v_cvt_pk_bf16_f32 v5, v5, v101
	v_cvt_pk_bf16_f32 v6, v6, v101
	v_cvt_pk_bf16_f32 v7, v7, v101
	ds_write_b16 v195, v0 offset:96
	ds_write_b16 v195, v1 offset:240
	ds_write_b16 v195, v2 offset:384
	ds_write_b16 v195, v3 offset:528
	ds_write_b16 v195, v4 offset:2400
	ds_write_b16 v195, v5 offset:2544
	ds_write_b16 v195, v6 offset:2688
	ds_write_b16 v195, v7 offset:2832
	v_ashrrev_i32_e32 v159, 31, v158
	v_lshlrev_b64 v[4:5], 10, v[158:159]
	s_waitcnt lgkmcnt(0)
	ds_read_b128 v[0:3], v196
	s_load_dwordx2 s[0:1], s[0:1], 0x110
	s_waitcnt lgkmcnt(0)
	v_lshl_add_u64 v[4:5], s[0:1], 0, v[4:5]
	v_lshl_add_u64 v[4:5], v[4:5], 0, s[10:11]
	v_lshl_add_u64 v[4:5], v[4:5], 0, v[100:101]
	v_add_co_u32_e32 v4, vcc, s47, v4
	s_mov_b64 s[0:1], s[80:81]
	s_nop 0
	v_addc_co_u32_e32 v5, vcc, 0, v5, vcc
	global_store_dwordx4 v[4:5], v[0:3], off
	ds_read_b128 v[0:3], v196 offset:1152
	s_load_dwordx2 s[0:1], s[0:1], 0x110
	v_add_u32_e32 v4, 8, v158
	v_ashrrev_i32_e32 v5, 31, v4
	v_lshlrev_b64 v[4:5], 10, v[4:5]
	s_waitcnt lgkmcnt(0)
	v_lshl_add_u64 v[4:5], s[0:1], 0, v[4:5]
	v_lshl_add_u64 v[4:5], v[4:5], 0, s[10:11]
	v_lshl_add_u64 v[4:5], v[4:5], 0, v[100:101]
	v_add_co_u32_e32 v4, vcc, s47, v4
	s_mov_b64 s[0:1], s[80:81]
	s_nop 0
	v_addc_co_u32_e32 v5, vcc, 0, v5, vcc
	global_store_dwordx4 v[4:5], v[0:3], off
	ds_read_b128 v[0:3], v196 offset:2304
	s_load_dwordx2 s[0:1], s[0:1], 0x110
	v_add_u32_e32 v4, 16, v158
	v_ashrrev_i32_e32 v5, 31, v4
	v_lshlrev_b64 v[4:5], 10, v[4:5]
	s_waitcnt lgkmcnt(0)
	v_lshl_add_u64 v[4:5], s[0:1], 0, v[4:5]
	v_lshl_add_u64 v[4:5], v[4:5], 0, s[10:11]
	v_lshl_add_u64 v[4:5], v[4:5], 0, v[100:101]
	v_add_co_u32_e32 v4, vcc, s47, v4
	s_mov_b64 s[0:1], s[80:81]
	s_nop 0
	v_addc_co_u32_e32 v5, vcc, 0, v5, vcc
	global_store_dwordx4 v[4:5], v[0:3], off
	ds_read_b128 v[0:3], v196 offset:3456
	s_load_dwordx2 s[0:1], s[0:1], 0x110
	v_add_u32_e32 v4, 24, v158
	v_ashrrev_i32_e32 v5, 31, v4
	v_lshlrev_b64 v[4:5], 10, v[4:5]
	s_waitcnt lgkmcnt(0)
	v_lshl_add_u64 v[4:5], s[0:1], 0, v[4:5]
	v_lshl_add_u64 v[4:5], v[4:5], 0, s[10:11]
	v_lshl_add_u64 v[4:5], v[4:5], 0, v[100:101]
	v_add_co_u32_e32 v4, vcc, 0x11300000, v4
	s_nop 1
	v_addc_co_u32_e32 v5, vcc, 0, v5, vcc
	global_store_dwordx4 v[4:5], v[0:3], off
	s_waitcnt lgkmcnt(0)
	s_cbranch_scc1 .LBB0_671
